# store-aware vmcnt at tile start also in the 5 residual-epilogue GEMM loops (vmcnt(24) in the first K iteration after an epilogue)
# speedup vs baseline: 1.0080x; 1.0025x over previous
; #define PG8_WAIT_V(n) asm volatile("s_waitcnt vmcnt(" #n ")" ::: "memory")
; template <class Epi, class Sched, bool ALIGN_EPI = false, bool SP2 = false, bool F16 = false, bool TOKPERM = false>
; __device__ __forceinline__ void gemm_phase(PG8_LAS unsigned char* lds, const Gemm g, const Sched& S, const Epi& E, int wv) {
;     ...
;     for (int i = 0; i < 2; ++i) { int R, C; stage_rc(tid * 16 + i * 8192, R, C); const int Rb = Epi::PERM ? ((R & ~31) + perm32(R & 31)) : R;
;         const int Ra = TOKPERM ? ((R & ~63) + 4 * (R & 15) + ((R >> 4) & 3)) : R;
;         voffA[i] = (unsigned)(Ra * K + C) * 2u; voffB[i] = (unsigned)(Rb * K + C) * 2u; }
;     const size_t kstep = (size_t)(BK * 2);
;     const size_t hstep = (size_t)HALF * K * 2;
;     const size_t tstep = 2 * hstep;
;     const unsigned ldsw = (unsigned)wid * 1024u;
;     const int aoff = lds_byte(wr * 64 + fr, fq * 8), boff = lds_byte(wc * 32 + fr, fq * 8);
;     ...
;     Unit cur, nxt; int ui = 0;
;     if (!S.next(0, cur)) return;
;     f32x4 acc[2][2][4][2];
; #pragma unroll
;     for (int a = 0; a < 2; ++a)
; #pragma unroll
;         for (int b = 0; b < 2; ++b)
; #pragma unroll
;             for (int m = 0; m < 4; ++m)
; #pragma unroll
;                 for (int n = 0; n < 2; ++n) acc[a][b][m][n] = (f32x4){0.f, 0.f, 0.f, 0.f};
;     bf16x8 At[4][2], B0[2][2], B1[2][2];
;     const char* cA = (const char*)g.A + (size_t)cur.pm * tstep; const char* cB = (const char*)g.Bt + (size_t)cur.pn * tstep;
;     S.a_ready(cur);
;     if constexpr (SP2) {
;         PG8_STAGE(PG8_SB(0, 0), cB, voffB); PG8_STAGE(PG8_SB(0, 1), cB + hstep, voffB); PG8_STAGE(PG8_SA(0, 0), cA, voffA); PG8_STAGE(PG8_SA(0, 1), cA + hstep, voffA);
;         if (wr == 1) PG8_BAR;
;         PG8_WAIT_V(2); PG8_BAR;
;         PG8_STAGE(PG8_SB(1, 0), cB + kstep, voffB); PG8_STAGE(PG8_SA(1, 0), cA + kstep, voffA); PG8_STAGE(PG8_SB(1, 1), cB + hstep + kstep, voffB);
;         PG8_WAIT_V(6); PG8_BAR;
;     } else {
;         PG8_STAGE(PG8_SB(0, 0), cB, voffB); PG8_STAGE(PG8_SA(0, 0), cA, voffA); PG8_STAGE(PG8_SB(0, 1), cB + hstep, voffB); PG8_STAGE(PG8_SA(0, 1), cA + hstep, voffA);
;         if (wr == 1) PG8_BAR;
;         PG8_WAIT_V(4); PG8_BAR;
;         PG8_STAGE(PG8_SB(1, 0), cB + kstep, voffB); PG8_STAGE(PG8_SA(1, 0), cA + kstep, voffA); PG8_STAGE(PG8_SB(1, 1), cB + hstep + kstep, voffB);
;         PG8_WAIT_V(6); PG8_BAR;
;     }
.LBB0_284:
	s_add_i32 s45, s2, 0x18000
	s_mov_b64 s[12:13], 0x80
	s_and_b32 s44, s4, 3
	v_lshl_add_u64 v[6:7], v[6:7], 0, s[12:13]
	s_mov_b32 m0, s45
	s_add_i32 s52, s2, 0x1a000
	s_lshl_b32 s4, s5, 13
	s_lshl_b32 s7, s44, 12
	s_waitcnt vmcnt(2)
	s_barrier
	global_load_lds_dwordx4 v[6:7], off
	v_lshl_add_u64 v[4:5], v[4:5], 0, s[12:13]
	s_mov_b32 m0, s52
	s_add_i32 s53, s2, 0x8000
	s_add_i32 s54, s2, 0xa000
	global_load_lds_dwordx4 v[4:5], off
	v_lshl_add_u64 v[2:3], v[2:3], 0, s[12:13]
	s_mov_b32 m0, s53
	s_add_u32 s8, s18, 0xb0080
	global_load_lds_dwordx4 v[2:3], off
	v_lshl_add_u64 v[0:1], v[0:1], 0, s[12:13]
	s_mov_b32 m0, s54
	s_addc_u32 s9, s19, 0
	s_add_i32 s55, s2, 0x1c000
	global_load_lds_dwordx4 v[0:1], off
	v_lshl_add_u64 v[0:1], s[8:9], 0, v[130:131]
	s_mov_b32 m0, s55
	s_add_i32 s56, s2, 0x1e000
	global_load_lds_dwordx4 v[0:1], off
	v_lshl_add_u64 v[0:1], s[8:9], 0, v[134:135]
	s_mov_b32 m0, s56
	s_mov_b64 s[8:9], 0xb0080
	global_load_lds_dwordx4 v[0:1], off
	v_bfe_u32 v0, v8, 4, 2
	v_and_b32_e32 v1, 15, v8
	v_lshlrev_b32_e32 v3, 4, v0
	v_lshl_or_b32 v146, s5, 6, v1
	v_lshl_or_b32 v1, v1, 6, v3
	v_lshlrev_b32_e32 v3, 2, v8
	v_and_b32_e32 v3, 32, v3
	v_lshlrev_b32_e32 v2, 3, v0
	v_bitop3_b32 v147, v1, s4, v3 bitop3:0xde
	v_bitop3_b32 v3, v1, s7, v3 bitop3:0xde
	v_cmp_eq_u32_e64 s[4:5], 0, v0
	v_lshrrev_b32_e32 v1, 1, v9
	v_mul_lo_u32 v0, v11, s6
	s_mov_b32 s7, 0xb000
	v_mad_u64_u32 v[0:1], s[10:11], v1, s7, v[0:1]
	v_or_b32_e32 v0, v0, v10
	v_add_lshl_u32 v136, v0, v12, 1
	v_lshrrev_b32_e32 v1, 1, v13
	v_mul_lo_u32 v0, v14, s6
	v_mad_u64_u32 v[0:1], s[6:7], v1, s7, v[0:1]
	s_waitcnt vmcnt(6)
	v_or_b32_e32 v0, v0, v15
	v_lshl_add_u64 v[138:139], v[136:137], 0, s[8:9]
	v_add_lshl_u32 v136, v0, v16, 1
	v_lshl_or_b32 v148, s44, 5, v2
	s_mov_b32 s57, 0
	s_ashr_i32 s58, s28, 31
	s_mov_b32 s59, s28
	s_ashr_i32 s60, s26, 31
	v_lshl_add_u64 v[140:141], v[136:137], 0, s[8:9]
	v_mov_b64_e32 v[142:143], 0x100
	v_mov_b64_e32 v[144:145], 0xff
	v_or_b32_e32 v149, 0x10000, v3
	v_add_u32_e32 v150, 0x10400, v3
	v_add_u32_e32 v151, 0x10800, v3
	v_add_u32_e32 v152, 0x10c00, v3
	v_or_b32_e32 v153, 0x14000, v3
	v_add_u32_e32 v154, 0x14400, v3
	v_add_u32_e32 v155, 0x14800, v3
	v_add_u32_e32 v156, 0x14c00, v3
	s_add_i32 s61, s2, 0xc000
	s_add_i32 s62, s2, 0xe000
	v_or_b32_e32 v157, 0x18000, v3
	v_add_u32_e32 v158, 0x18400, v3
	v_add_u32_e32 v159, 0x18800, v3
	v_add_u32_e32 v160, 0x18c00, v3
	v_or_b32_e32 v161, 0x1c000, v3
	v_add_u32_e32 v162, 0x1c400, v3
	v_add_u32_e32 v163, 0x1c800, v3
	v_add_u32_e32 v164, 0x1cc00, v3
	v_mbcnt_hi_u32_b32 v165, -1, v226
	s_barrier
	s_mov_b32 s99, 0
	s_branch .LBB0_286

; #define PG8_STAGE(bufoff, gbase, voff) do { _Pragma("unroll") for (int _i = 0; _i < 2; ++_i) \
;         __builtin_amdgcn_global_load_lds((const unsigned*)((const char*)(gbase) + (voff)[_i]), (PG8_LAS unsigned*)(lds + (bufoff) + ldsw + _i * 8192), 16, 0, 0); } while (0)
; #define PG8_LDA(dst, b, h) do { _Pragma("unroll") for (int m = 0; m < 4; ++m) _Pragma("unroll") for (int k = 0; k < 2; ++k) dst[m][k] = *(const PG8_LAS bf16x8*)(lds + PG8_SA(b, h) + aoff + m * 2048 + k * 1024); } while (0)
; #define PG8_LDB(dst, b, h) do { _Pragma("unroll") for (int n = 0; n < 2; ++n) _Pragma("unroll") for (int k = 0; k < 2; ++k) dst[n][k] = *(const PG8_LAS bf16x8*)(lds + PG8_SB(b, h) + boff + n * 2048 + k * 1024); } while (0)
; #define PG8_MMA(ai, bj, At, Bt) do { __builtin_amdgcn_s_setprio(1); _Pragma("unroll") for (int m = 0; m < 4; ++m) _Pragma("unroll") for (int n = 0; n < 2; ++n) _Pragma("unroll") for (int k = 0; k < 2; ++k) \
;         acc[ai][bj][m][n] = mma16<F16>(Bt[n][k], At[m][k], acc[ai][bj][m][n]); __builtin_amdgcn_s_setprio(0); } while (0)
; #define PG8_WAIT_V(n) asm volatile("s_waitcnt vmcnt(" #n ")" ::: "memory")
; #define PG8_WAIT_L(n) asm volatile("s_waitcnt lgkmcnt(" #n ")" ::: "memory")
; #define PG8_BAR __builtin_amdgcn_s_barrier()
; #define PG8_SCHED __builtin_amdgcn_sched_barrier(0)
; template <class Epi, class Sched, bool ALIGN_EPI = false, bool SP2 = false, bool F16 = false, bool TOKPERM = false>
; __device__ __forceinline__ void gemm_phase(PG8_LAS unsigned char* lds, const Gemm g, const Sched& S, const Epi& E, int wv) {
;     ...
;             PG8_LDB(B0, 0, 0); PG8_LDB(B1, 0, 1); PG8_SCHED; PG8_LDA(At, 0, 0); PG8_STAGE(PG8_SA(1, 1), a1 + hstep, voffA);
;             PG8_WAIT_V(8); PG8_WAIT_L(0); PG8_BAR; PG8_MMA(0, 0, At, B0); PG8_MMA(0, 1, At, B1); PG8_BAR; PG8_SCHED;
;             PG8_LDA(At, 0, 1); PG8_STAGE(PG8_SB(0, 0), b2, voffB); PG8_STAGE(PG8_SB(0, 1), b2 + hstep, voffB); PG8_STAGE(PG8_SA(0, 0), a2, voffA);
;             PG8_WAIT_V(8); PG8_WAIT_L(0); PG8_BAR; PG8_MMA(1, 0, At, B0); PG8_MMA(1, 1, At, B1); PG8_BAR; PG8_SCHED;
.LBB0_297:
	ds_read_b128 v[166:169], v149
	ds_read_b128 v[170:173], v150
	ds_read_b128 v[174:177], v151
	ds_read_b128 v[178:181], v152
	ds_read_b128 v[182:185], v153
	ds_read_b128 v[186:189], v154
	ds_read_b128 v[190:193], v155
	ds_read_b128 v[194:197], v156
	s_add_u32 s18, s16, 0x100
	s_addc_u32 s19, s17, 0
	s_cmp_eq_u32 s70, 40
	s_cselect_b32 s51, s9, s19
	s_cselect_b32 s50, s8, s18
	s_cselect_b32 s49, s11, s69
	s_cselect_b32 s48, s10, s68
	s_mov_b32 m0, s61
	v_lshl_add_u64 v[232:233], s[16:17], 0, v[138:139]
	ds_read_b128 v[198:201], v147
	ds_read_b128 v[202:205], v147 offset:1024
	ds_read_b128 v[206:209], v147 offset:2048
	ds_read_b128 v[210:213], v147 offset:3072
	ds_read_b128 v[214:217], v147 offset:4096
	ds_read_b128 v[218:221], v147 offset:5120
	ds_read_b128 v[222:225], v147 offset:6144
	ds_read_b128 v[228:231], v147 offset:7168
	global_load_lds_dwordx4 v[232:233], off
	v_lshl_add_u64 v[232:233], s[16:17], 0, v[140:141]
	s_mov_b32 m0, s62
	s_nop 0
	global_load_lds_dwordx4 v[232:233], off
	s_waitcnt vmcnt(24)
	s_cmp_eq_u32 s99, 1
	s_cbranch_scc1 .Lvmw_297_0
	s_waitcnt vmcnt(8)
.Lvmw_297_0:
	s_waitcnt lgkmcnt(0)
	s_barrier
	s_setprio 1
	s_waitcnt lgkmcnt(0)
	v_mfma_f32_16x16x32_bf16 v[124:127], v[166:169], v[198:201], v[124:127]
	v_mfma_f32_16x16x32_bf16 v[120:123], v[174:177], v[198:201], v[120:123]
	v_mfma_f32_16x16x32_bf16 v[108:111], v[166:169], v[206:209], v[108:111]
	v_mfma_f32_16x16x32_bf16 v[104:107], v[174:177], v[206:209], v[104:107]
	v_mfma_f32_16x16x32_bf16 v[92:95], v[166:169], v[214:217], v[92:95]
	v_mfma_f32_16x16x32_bf16 v[88:91], v[174:177], v[214:217], v[88:91]
	v_mfma_f32_16x16x32_bf16 v[76:79], v[166:169], v[222:225], v[76:79]
	v_mfma_f32_16x16x32_bf16 v[72:75], v[174:177], v[222:225], v[72:75]
	v_mfma_f32_16x16x32_bf16 v[124:127], v[170:173], v[202:205], v[124:127]
	v_mfma_f32_16x16x32_bf16 v[120:123], v[178:181], v[202:205], v[120:123]
	v_mfma_f32_16x16x32_bf16 v[108:111], v[170:173], v[210:213], v[108:111]
	v_mfma_f32_16x16x32_bf16 v[104:107], v[178:181], v[210:213], v[104:107]
	v_mfma_f32_16x16x32_bf16 v[92:95], v[170:173], v[218:221], v[92:95]
	v_mfma_f32_16x16x32_bf16 v[88:91], v[178:181], v[218:221], v[88:91]
	v_mfma_f32_16x16x32_bf16 v[76:79], v[170:173], v[228:231], v[76:79]
	v_mfma_f32_16x16x32_bf16 v[72:75], v[178:181], v[228:231], v[72:75]
	s_setprio 0
	s_setprio 1
	v_mfma_f32_16x16x32_bf16 v[116:119], v[182:185], v[198:201], v[116:119]
	v_mfma_f32_16x16x32_bf16 v[112:115], v[190:193], v[198:201], v[112:115]
	v_mfma_f32_16x16x32_bf16 v[100:103], v[182:185], v[206:209], v[100:103]
	v_mfma_f32_16x16x32_bf16 v[96:99], v[190:193], v[206:209], v[96:99]
	v_mfma_f32_16x16x32_bf16 v[84:87], v[182:185], v[214:217], v[84:87]
	v_mfma_f32_16x16x32_bf16 v[80:83], v[190:193], v[214:217], v[80:83]
	v_mfma_f32_16x16x32_bf16 v[68:71], v[182:185], v[222:225], v[68:71]
	v_mfma_f32_16x16x32_bf16 v[64:67], v[190:193], v[222:225], v[64:67]
	v_mfma_f32_16x16x32_bf16 v[116:119], v[186:189], v[202:205], v[116:119]
	v_mfma_f32_16x16x32_bf16 v[112:115], v[194:197], v[202:205], v[112:115]
	v_mfma_f32_16x16x32_bf16 v[100:103], v[186:189], v[210:213], v[100:103]
	v_mfma_f32_16x16x32_bf16 v[96:99], v[194:197], v[210:213], v[96:99]
	v_mfma_f32_16x16x32_bf16 v[84:87], v[186:189], v[218:221], v[84:87]
	v_mfma_f32_16x16x32_bf16 v[80:83], v[194:197], v[218:221], v[80:83]
	v_mfma_f32_16x16x32_bf16 v[68:71], v[186:189], v[228:231], v[68:71]
	v_mfma_f32_16x16x32_bf16 v[64:67], v[194:197], v[228:231], v[64:67]
	s_setprio 0
	s_barrier
	s_mov_b32 m0, s3
	v_lshl_add_u64 v[232:233], s[48:49], 0, v[130:131]
	s_add_u32 s16, s48, 0xb0000
	ds_read_b128 v[198:201], v147 offset:16384
	ds_read_b128 v[202:205], v147 offset:17408
	ds_read_b128 v[206:209], v147 offset:18432
	ds_read_b128 v[210:213], v147 offset:19456
	ds_read_b128 v[214:217], v147 offset:20480
	ds_read_b128 v[218:221], v147 offset:21504
	ds_read_b128 v[222:225], v147 offset:22528
	ds_read_b128 v[228:231], v147 offset:23552
	global_load_lds_dwordx4 v[232:233], off
	v_lshl_add_u64 v[234:235], s[48:49], 0, v[134:135]
	s_mov_b32 m0, s21
	s_addc_u32 s17, s49, 0
	global_load_lds_dwordx4 v[234:235], off
	v_lshl_add_u64 v[236:237], s[16:17], 0, v[130:131]
	s_mov_b32 m0, s22
	v_lshl_add_u64 v[238:239], s[50:51], 0, v[132:133]
	global_load_lds_dwordx4 v[236:237], off
	v_lshl_add_u64 v[236:237], s[16:17], 0, v[134:135]
	s_mov_b32 m0, s23
	s_nop 0
	global_load_lds_dwordx4 v[236:237], off
	v_lshl_add_u64 v[236:237], s[50:51], 0, v[128:129]
	s_mov_b32 m0, s2
	s_nop 0
	global_load_lds_dwordx4 v[236:237], off
	s_mov_b32 m0, s33
	s_nop 0
	global_load_lds_dwordx4 v[238:239], off
	s_waitcnt vmcnt(24)
	s_cmp_eq_u32 s99, 1
	s_cbranch_scc1 .Lvmw_297_1
	s_waitcnt vmcnt(8)
; #define PG8_STAGE(bufoff, gbase, voff) do { _Pragma("unroll") for (int _i = 0; _i < 2; ++_i) \
;         __builtin_amdgcn_global_load_lds((const unsigned*)((const char*)(gbase) + (voff)[_i]), (PG8_LAS unsigned*)(lds + (bufoff) + ldsw + _i * 8192), 16, 0, 0); } while (0)
; #define PG8_LDA(dst, b, h) do { _Pragma("unroll") for (int m = 0; m < 4; ++m) _Pragma("unroll") for (int k = 0; k < 2; ++k) dst[m][k] = *(const PG8_LAS bf16x8*)(lds + PG8_SA(b, h) + aoff + m * 2048 + k * 1024); } while (0)
; #define PG8_LDB(dst, b, h) do { _Pragma("unroll") for (int n = 0; n < 2; ++n) _Pragma("unroll") for (int k = 0; k < 2; ++k) dst[n][k] = *(const PG8_LAS bf16x8*)(lds + PG8_SB(b, h) + boff + n * 2048 + k * 1024); } while (0)
; #define PG8_MMA(ai, bj, At, Bt) do { __builtin_amdgcn_s_setprio(1); _Pragma("unroll") for (int m = 0; m < 4; ++m) _Pragma("unroll") for (int n = 0; n < 2; ++n) _Pragma("unroll") for (int k = 0; k < 2; ++k) \
;         acc[ai][bj][m][n] = mma16<F16>(Bt[n][k], At[m][k], acc[ai][bj][m][n]); __builtin_amdgcn_s_setprio(0); } while (0)
; #define PG8_WAIT_V(n) asm volatile("s_waitcnt vmcnt(" #n ")" ::: "memory")
; #define PG8_WAIT_L(n) asm volatile("s_waitcnt lgkmcnt(" #n ")" ::: "memory")
; #define PG8_BAR __builtin_amdgcn_s_barrier()
; #define PG8_SCHED __builtin_amdgcn_sched_barrier(0)
; template <class Epi, class Sched, bool ALIGN_EPI = false, bool SP2 = false, bool F16 = false, bool TOKPERM = false>
; __device__ __forceinline__ void gemm_phase(PG8_LAS unsigned char* lds, const Gemm g, const Sched& S, const Epi& E, int wv) {
;     ...
;             PG8_WAIT_V(8); PG8_WAIT_L(0); PG8_BAR; PG8_MMA(1, 0, At, B0); PG8_MMA(1, 1, At, B1); PG8_BAR; PG8_SCHED;
;             PG8_LDB(B0, 1, 0); PG8_LDB(B1, 1, 1); PG8_SCHED; PG8_LDA(At, 1, 0); PG8_STAGE(PG8_SA(0, 1), a2 + hstep, voffA);
;             PG8_WAIT_V(8); PG8_WAIT_L(0); PG8_BAR; PG8_MMA(0, 0, At, B0); PG8_MMA(0, 1, At, B1); PG8_BAR; PG8_SCHED;
.Lvmw_297_1:
	s_mov_b32 s99, 0
	s_waitcnt lgkmcnt(0)
	s_barrier
	s_setprio 1
	s_waitcnt lgkmcnt(0)
	v_mfma_f32_16x16x32_bf16 v[60:63], v[166:169], v[198:201], v[60:63]
	v_mfma_f32_16x16x32_bf16 v[56:59], v[174:177], v[198:201], v[56:59]
	v_mfma_f32_16x16x32_bf16 v[44:47], v[166:169], v[206:209], v[44:47]
	v_mfma_f32_16x16x32_bf16 v[40:43], v[174:177], v[206:209], v[40:43]
	v_mfma_f32_16x16x32_bf16 v[28:31], v[166:169], v[214:217], v[28:31]
	v_mfma_f32_16x16x32_bf16 v[24:27], v[174:177], v[214:217], v[24:27]
	v_mfma_f32_16x16x32_bf16 v[12:15], v[166:169], v[222:225], v[12:15]
	v_mfma_f32_16x16x32_bf16 v[8:11], v[174:177], v[222:225], v[8:11]
	v_mfma_f32_16x16x32_bf16 v[60:63], v[170:173], v[202:205], v[60:63]
	v_mfma_f32_16x16x32_bf16 v[56:59], v[178:181], v[202:205], v[56:59]
	v_mfma_f32_16x16x32_bf16 v[44:47], v[170:173], v[210:213], v[44:47]
	v_mfma_f32_16x16x32_bf16 v[40:43], v[178:181], v[210:213], v[40:43]
	v_mfma_f32_16x16x32_bf16 v[28:31], v[170:173], v[218:221], v[28:31]
	v_mfma_f32_16x16x32_bf16 v[24:27], v[178:181], v[218:221], v[24:27]
	v_mfma_f32_16x16x32_bf16 v[12:15], v[170:173], v[228:231], v[12:15]
	v_mfma_f32_16x16x32_bf16 v[8:11], v[178:181], v[228:231], v[8:11]
	s_setprio 0
	s_setprio 1
	v_mfma_f32_16x16x32_bf16 v[52:55], v[182:185], v[198:201], v[52:55]
	v_mfma_f32_16x16x32_bf16 v[48:51], v[190:193], v[198:201], v[48:51]
	v_mfma_f32_16x16x32_bf16 v[36:39], v[182:185], v[206:209], v[36:39]
	v_mfma_f32_16x16x32_bf16 v[32:35], v[190:193], v[206:209], v[32:35]
	v_mfma_f32_16x16x32_bf16 v[20:23], v[182:185], v[214:217], v[20:23]
	v_mfma_f32_16x16x32_bf16 v[16:19], v[190:193], v[214:217], v[16:19]
	v_mfma_f32_16x16x32_bf16 v[4:7], v[182:185], v[222:225], v[4:7]
	v_mfma_f32_16x16x32_bf16 v[0:3], v[190:193], v[222:225], v[0:3]
	v_mfma_f32_16x16x32_bf16 v[52:55], v[186:189], v[202:205], v[52:55]
	v_mfma_f32_16x16x32_bf16 v[48:51], v[194:197], v[202:205], v[48:51]
	v_mfma_f32_16x16x32_bf16 v[36:39], v[186:189], v[210:213], v[36:39]
	v_mfma_f32_16x16x32_bf16 v[32:35], v[194:197], v[210:213], v[32:35]
	v_mfma_f32_16x16x32_bf16 v[20:23], v[186:189], v[218:221], v[20:23]
	v_mfma_f32_16x16x32_bf16 v[16:19], v[194:197], v[218:221], v[16:19]
	v_mfma_f32_16x16x32_bf16 v[4:7], v[186:189], v[228:231], v[4:7]
	v_mfma_f32_16x16x32_bf16 v[0:3], v[194:197], v[228:231], v[0:3]
	s_setprio 0
	s_barrier
	ds_read_b128 v[166:169], v157
	ds_read_b128 v[170:173], v158
	ds_read_b128 v[174:177], v159
	ds_read_b128 v[178:181], v160
	ds_read_b128 v[182:185], v161
	ds_read_b128 v[186:189], v162
	ds_read_b128 v[190:193], v163
	ds_read_b128 v[194:197], v164
	s_add_u32 s16, s50, 0xb0000
	s_addc_u32 s17, s51, 0
	s_mov_b32 m0, s36
	v_lshl_add_u64 v[240:241], s[16:17], 0, v[128:129]
	ds_read_b128 v[198:201], v147 offset:32768
	ds_read_b128 v[202:205], v147 offset:33792
	ds_read_b128 v[206:209], v147 offset:34816
	ds_read_b128 v[210:213], v147 offset:35840
	ds_read_b128 v[214:217], v147 offset:36864
	ds_read_b128 v[218:221], v147 offset:37888
	ds_read_b128 v[222:225], v147 offset:38912
	ds_read_b128 v[228:231], v147 offset:39936
	global_load_lds_dwordx4 v[240:241], off
	v_lshl_add_u64 v[240:241], s[16:17], 0, v[132:133]
	s_mov_b32 m0, s37
	s_nop 0
	global_load_lds_dwordx4 v[240:241], off
	s_waitcnt vmcnt(8)
	s_waitcnt lgkmcnt(0)
	s_barrier
	s_setprio 1
	s_waitcnt lgkmcnt(0)
	v_mfma_f32_16x16x32_bf16 v[124:127], v[166:169], v[198:201], v[124:127]
	v_mfma_f32_16x16x32_bf16 v[120:123], v[174:177], v[198:201], v[120:123]
	v_mfma_f32_16x16x32_bf16 v[108:111], v[166:169], v[206:209], v[108:111]
	v_mfma_f32_16x16x32_bf16 v[104:107], v[174:177], v[206:209], v[104:107]
	v_mfma_f32_16x16x32_bf16 v[92:95], v[166:169], v[214:217], v[92:95]
	v_mfma_f32_16x16x32_bf16 v[88:91], v[174:177], v[214:217], v[88:91]
	v_mfma_f32_16x16x32_bf16 v[76:79], v[166:169], v[222:225], v[76:79]
	v_mfma_f32_16x16x32_bf16 v[72:75], v[174:177], v[222:225], v[72:75]
	v_mfma_f32_16x16x32_bf16 v[124:127], v[170:173], v[202:205], v[124:127]
	v_mfma_f32_16x16x32_bf16 v[120:123], v[178:181], v[202:205], v[120:123]
	v_mfma_f32_16x16x32_bf16 v[108:111], v[170:173], v[210:213], v[108:111]
	v_mfma_f32_16x16x32_bf16 v[104:107], v[178:181], v[210:213], v[104:107]
	v_mfma_f32_16x16x32_bf16 v[92:95], v[170:173], v[218:221], v[92:95]
	v_mfma_f32_16x16x32_bf16 v[88:91], v[178:181], v[218:221], v[88:91]
	v_mfma_f32_16x16x32_bf16 v[76:79], v[170:173], v[228:231], v[76:79]
	v_mfma_f32_16x16x32_bf16 v[72:75], v[178:181], v[228:231], v[72:75]
	s_setprio 0
	s_setprio 1
	v_mfma_f32_16x16x32_bf16 v[116:119], v[182:185], v[198:201], v[116:119]
	v_mfma_f32_16x16x32_bf16 v[112:115], v[190:193], v[198:201], v[112:115]
	v_mfma_f32_16x16x32_bf16 v[100:103], v[182:185], v[206:209], v[100:103]
	v_mfma_f32_16x16x32_bf16 v[96:99], v[190:193], v[206:209], v[96:99]
	v_mfma_f32_16x16x32_bf16 v[84:87], v[182:185], v[214:217], v[84:87]
	v_mfma_f32_16x16x32_bf16 v[80:83], v[190:193], v[214:217], v[80:83]
	v_mfma_f32_16x16x32_bf16 v[68:71], v[182:185], v[222:225], v[68:71]
	v_mfma_f32_16x16x32_bf16 v[64:67], v[190:193], v[222:225], v[64:67]
	v_mfma_f32_16x16x32_bf16 v[116:119], v[186:189], v[202:205], v[116:119]
	v_mfma_f32_16x16x32_bf16 v[112:115], v[194:197], v[202:205], v[112:115]
	v_mfma_f32_16x16x32_bf16 v[100:103], v[186:189], v[210:213], v[100:103]
	v_mfma_f32_16x16x32_bf16 v[96:99], v[194:197], v[210:213], v[96:99]
	v_mfma_f32_16x16x32_bf16 v[84:87], v[186:189], v[218:221], v[84:87]
	v_mfma_f32_16x16x32_bf16 v[80:83], v[194:197], v[218:221], v[80:83]
	v_mfma_f32_16x16x32_bf16 v[68:71], v[186:189], v[228:231], v[68:71]
	v_mfma_f32_16x16x32_bf16 v[64:67], v[194:197], v[228:231], v[64:67]
	s_setprio 0
	s_barrier
; #define PG8_STAGE(bufoff, gbase, voff) do { _Pragma("unroll") for (int _i = 0; _i < 2; ++_i) \
;         __builtin_amdgcn_global_load_lds((const unsigned*)((const char*)(gbase) + (voff)[_i]), (PG8_LAS unsigned*)(lds + (bufoff) + ldsw + _i * 8192), 16, 0, 0); } while (0)
; #define PG8_LDA(dst, b, h) do { _Pragma("unroll") for (int m = 0; m < 4; ++m) _Pragma("unroll") for (int k = 0; k < 2; ++k) dst[m][k] = *(const PG8_LAS bf16x8*)(lds + PG8_SA(b, h) + aoff + m * 2048 + k * 1024); } while (0)
; #define PG8_MMA(ai, bj, At, Bt) do { __builtin_amdgcn_s_setprio(1); _Pragma("unroll") for (int m = 0; m < 4; ++m) _Pragma("unroll") for (int n = 0; n < 2; ++n) _Pragma("unroll") for (int k = 0; k < 2; ++k) \
;         acc[ai][bj][m][n] = mma16<F16>(Bt[n][k], At[m][k], acc[ai][bj][m][n]); __builtin_amdgcn_s_setprio(0); } while (0)
; #define PG8_WAIT_V(n) asm volatile("s_waitcnt vmcnt(" #n ")" ::: "memory")
; #define PG8_WAIT_L(n) asm volatile("s_waitcnt lgkmcnt(" #n ")" ::: "memory")
; #define PG8_BAR __builtin_amdgcn_s_barrier()
; #define PG8_SCHED __builtin_amdgcn_sched_barrier(0)
; template <class Epi, class Sched, bool ALIGN_EPI = false, bool SP2 = false, bool F16 = false, bool TOKPERM = false>
; __device__ __forceinline__ void gemm_phase(PG8_LAS unsigned char* lds, const Gemm g, const Sched& S, const Epi& E, int wv) {
;     ...
;             PG8_LDA(At, 1, 1); PG8_STAGE(PG8_SB(1, 0), b3, voffB); PG8_STAGE(PG8_SB(1, 1), b3 + hstep, voffB); PG8_STAGE(PG8_SA(1, 0), a3, voffA);
;             PG8_WAIT_V(8); PG8_WAIT_L(0); PG8_BAR; PG8_MMA(1, 0, At, B0); PG8_MMA(1, 1, At, B1); PG8_BAR; PG8_SCHED;
	s_mov_b32 m0, s45
	v_lshl_add_u64 v[232:233], v[232:233], 0, s[12:13]
	s_add_u32 s16, s48, 0xb0080
	ds_read_b128 v[198:201], v147 offset:49152
	ds_read_b128 v[202:205], v147 offset:50176
	ds_read_b128 v[206:209], v147 offset:51200
	ds_read_b128 v[210:213], v147 offset:52224
	ds_read_b128 v[214:217], v147 offset:53248
	ds_read_b128 v[218:221], v147 offset:54272
	ds_read_b128 v[222:225], v147 offset:55296
	ds_read_b128 v[228:231], v147 offset:56320
	global_load_lds_dwordx4 v[232:233], off
	v_lshl_add_u64 v[232:233], v[234:235], 0, s[12:13]
	s_mov_b32 m0, s52
	s_addc_u32 s17, s49, 0
	global_load_lds_dwordx4 v[232:233], off
	v_lshl_add_u64 v[232:233], s[16:17], 0, v[130:131]
	s_mov_b32 m0, s55
	s_nop 0
	global_load_lds_dwordx4 v[232:233], off
	v_lshl_add_u64 v[232:233], s[16:17], 0, v[134:135]
	s_mov_b32 m0, s56
	s_nop 0
	global_load_lds_dwordx4 v[232:233], off
	v_lshl_add_u64 v[232:233], v[236:237], 0, s[12:13]
	s_mov_b32 m0, s53
	s_nop 0
	global_load_lds_dwordx4 v[232:233], off
	v_lshl_add_u64 v[232:233], v[238:239], 0, s[12:13]
	s_mov_b32 m0, s54
	s_nop 0
	global_load_lds_dwordx4 v[232:233], off
	s_waitcnt vmcnt(8)
	s_waitcnt lgkmcnt(0)
	s_barrier
	s_setprio 1
	s_waitcnt lgkmcnt(0)
	v_mfma_f32_16x16x32_bf16 v[60:63], v[166:169], v[198:201], v[60:63]
	v_mfma_f32_16x16x32_bf16 v[56:59], v[174:177], v[198:201], v[56:59]
	v_mfma_f32_16x16x32_bf16 v[44:47], v[166:169], v[206:209], v[44:47]
	v_mfma_f32_16x16x32_bf16 v[40:43], v[174:177], v[206:209], v[40:43]
	v_mfma_f32_16x16x32_bf16 v[28:31], v[166:169], v[214:217], v[28:31]
	v_mfma_f32_16x16x32_bf16 v[24:27], v[174:177], v[214:217], v[24:27]
	v_mfma_f32_16x16x32_bf16 v[12:15], v[166:169], v[222:225], v[12:15]
	v_mfma_f32_16x16x32_bf16 v[8:11], v[174:177], v[222:225], v[8:11]
	v_mfma_f32_16x16x32_bf16 v[60:63], v[170:173], v[202:205], v[60:63]
	v_mfma_f32_16x16x32_bf16 v[56:59], v[178:181], v[202:205], v[56:59]
	v_mfma_f32_16x16x32_bf16 v[44:47], v[170:173], v[210:213], v[44:47]
	v_mfma_f32_16x16x32_bf16 v[40:43], v[178:181], v[210:213], v[40:43]
	v_mfma_f32_16x16x32_bf16 v[28:31], v[170:173], v[218:221], v[28:31]
	v_mfma_f32_16x16x32_bf16 v[24:27], v[178:181], v[218:221], v[24:27]
	v_mfma_f32_16x16x32_bf16 v[12:15], v[170:173], v[228:231], v[12:15]
	v_mfma_f32_16x16x32_bf16 v[8:11], v[178:181], v[228:231], v[8:11]
	s_setprio 0
	s_setprio 1
	v_mfma_f32_16x16x32_bf16 v[52:55], v[182:185], v[198:201], v[52:55]
	v_mfma_f32_16x16x32_bf16 v[48:51], v[190:193], v[198:201], v[48:51]
	v_mfma_f32_16x16x32_bf16 v[36:39], v[182:185], v[206:209], v[36:39]
	v_mfma_f32_16x16x32_bf16 v[32:35], v[190:193], v[206:209], v[32:35]
	v_mfma_f32_16x16x32_bf16 v[20:23], v[182:185], v[214:217], v[20:23]
	v_mfma_f32_16x16x32_bf16 v[16:19], v[190:193], v[214:217], v[16:19]
	v_mfma_f32_16x16x32_bf16 v[4:7], v[182:185], v[222:225], v[4:7]
	v_mfma_f32_16x16x32_bf16 v[0:3], v[190:193], v[222:225], v[0:3]
	v_mfma_f32_16x16x32_bf16 v[52:55], v[186:189], v[202:205], v[52:55]
	v_mfma_f32_16x16x32_bf16 v[48:51], v[194:197], v[202:205], v[48:51]
	v_mfma_f32_16x16x32_bf16 v[36:39], v[186:189], v[210:213], v[36:39]
	v_mfma_f32_16x16x32_bf16 v[32:35], v[194:197], v[210:213], v[32:35]
	v_mfma_f32_16x16x32_bf16 v[20:23], v[186:189], v[218:221], v[20:23]
	v_mfma_f32_16x16x32_bf16 v[16:19], v[194:197], v[218:221], v[16:19]
	v_mfma_f32_16x16x32_bf16 v[4:7], v[186:189], v[228:231], v[4:7]
	v_mfma_f32_16x16x32_bf16 v[0:3], v[194:197], v[228:231], v[0:3]
	s_setprio 0
	s_barrier
	s_add_i32 s70, s70, 2
	s_add_u32 s68, s68, 0x100
	s_addc_u32 s69, s69, 0
	s_cmp_gt_u32 s70, 41
	s_mov_b64 s[16:17], s[18:19]
	s_cbranch_scc0 .LBB0_297
;   __device__ __forceinline__ void operator()(const pg8::f32x4 (&acc)[2][2][4][2], const pg8::Unit& u, int wr, int wc, int fr, int fq) const {
;     int z; asm volatile("v_mov_b32 %0, 0" : "=v"(z));
;     const int row0 = u.pm * 256 + wr * 64 + fr + z, colb = u.pn * 256 + wc * 32 + 8 * fq + z;
; #pragma unroll
;     for (int ai = 0; ai < 2; ++ai)
; #pragma unroll
;       for (int m = 0; m < 4; ++m) {
;         const int tok = row0 + ai * 128 + m * 16; float ss = 0.f;
; #pragma unroll
;         for (int bj = 0; bj < 2; ++bj) {
;           const unsigned off = (unsigned)tok * DM + colb + 128 * bj;
;           f8_t n = __builtin_convertvector(*(const h8_t*)(x16 + off), f8_t);
; #pragma unroll
;           for (int c = 0; c < 4; ++c) { n[c] += sc * acc[ai][bj][m][0][c]; n[4 + c] += sc * acc[ai][bj][m][1][c]; }
;           if (aux) {
;             *(h8_t*)(x16 + off) = __builtin_convertvector(n, h8_t);
;             ss += ((n[0] * n[0] + n[1] * n[1]) + (n[2] * n[2] + n[3] * n[3])) + ((n[4] * n[4] + n[5] * n[5]) + (n[6] * n[6] + n[7] * n[7]));
;           } else {
;             *(f32x4*)(xout + off) = (f32x4){n[0], n[1], n[2], n[3]}; *(f32x4*)(xout + off + 4) = (f32x4){n[4], n[5], n[6], n[7]};
;           }
;         }
;         if (aux) { ss += __shfl_xor(ss, 16); ss += __shfl_xor(ss, 32); if (fq == 0) ssq[(unsigned)tok * 16 + u.pn * 4 + wc] = ss; }
;         if (m & 1) asm volatile("" ::: "memory");
;       }
;   }
	s_mov_b32 s99, 1
	s_lshl_b32 s16, s66, 8
	v_lshl_or_b32 v166, s65, 8, v148
	v_mov_b32 v136, 0
	v_xor_b32_e32 v169, 32, v165
	v_add3_u32 v167, s16, v146, v136
	v_add_u32_e32 v168, v166, v136
	v_lshl_add_u32 v136, v167, 10, v168
	v_lshl_add_u64 v[178:179], v[136:137], 1, s[40:41]
	v_add_u32_e32 v136, 0x80, v136
	global_load_dwordx4 v[170:173], v[178:179], off
	v_lshl_add_u64 v[180:181], v[136:137], 1, s[40:41]
	global_load_dwordx4 v[174:177], v[180:181], off
	v_add_u32_e32 v136, 16, v167
	v_lshl_add_u32 v136, v136, 10, v168
	v_lshl_add_u64 v[224:225], v[136:137], 1, s[40:41]
	v_add_u32_e32 v136, 0x80, v136
	global_load_dwordx4 v[192:195], v[224:225], off
	v_lshl_add_u64 v[248:249], v[136:137], 1, s[40:41]
	global_load_dwordx4 v[196:199], v[248:249], off
	v_add_u32_e32 v136, 32, v167
	v_lshl_add_u32 v136, v136, 10, v168
	v_lshl_add_u64 v[224:225], v[136:137], 1, s[40:41]
	v_add_u32_e32 v136, 0x80, v136
	global_load_dwordx4 v[200:203], v[224:225], off
	v_lshl_add_u64 v[248:249], v[136:137], 1, s[40:41]
	global_load_dwordx4 v[204:207], v[248:249], off
	v_add_u32_e32 v136, 48, v167
	v_lshl_add_u32 v136, v136, 10, v168
	v_lshl_add_u64 v[224:225], v[136:137], 1, s[40:41]
	v_add_u32_e32 v136, 0x80, v136
	global_load_dwordx4 v[208:211], v[224:225], off
	v_lshl_add_u64 v[248:249], v[136:137], 1, s[40:41]
	global_load_dwordx4 v[212:215], v[248:249], off
	v_add_u32_e32 v136, 0x80, v167
	v_lshl_add_u32 v136, v136, 10, v168
	v_lshl_add_u64 v[224:225], v[136:137], 1, s[40:41]
	v_add_u32_e32 v136, 0x80, v136
	global_load_dwordx4 v[216:219], v[224:225], off
	v_lshl_add_u64 v[248:249], v[136:137], 1, s[40:41]
	global_load_dwordx4 v[220:223], v[248:249], off
	v_add_u32_e32 v136, 0x90, v167
	v_lshl_add_u32 v136, v136, 10, v168
	v_lshl_add_u64 v[224:225], v[136:137], 1, s[40:41]
	v_add_u32_e32 v136, 0x80, v136
	global_load_dwordx4 v[228:231], v[224:225], off
	v_lshl_add_u64 v[248:249], v[136:137], 1, s[40:41]
	global_load_dwordx4 v[244:247], v[248:249], off
	v_and_b32_e32 v166, 64, v165
	v_xor_b32_e32 v136, 16, v165
	v_add_u32_e32 v166, 64, v166
	v_cmp_lt_i32_e32 vcc, v136, v166
	s_lshl_b32 s16, s65, 2
	s_or_b32 s18, s16, s44
	v_cndmask_b32_e32 v136, v165, v136, vcc
	v_cmp_lt_i32_e32 vcc, v169, v166
	v_lshlrev_b32_e32 v166, 2, v136
	s_waitcnt vmcnt(10)
	v_cvt_f32_f16_e32 v182, v173
	v_cvt_f32_f16_sdwa v183, v173 dst_sel:DWORD dst_unused:UNUSED_PAD src0_sel:WORD_1
	v_cvt_f32_f16_e32 v184, v171
	v_cvt_f32_f16_sdwa v185, v171 dst_sel:DWORD dst_unused:UNUSED_PAD src0_sel:WORD_1
	v_cvt_f32_f16_e32 v186, v172
	v_cvt_f32_f16_sdwa v187, v172 dst_sel:DWORD dst_unused:UNUSED_PAD src0_sel:WORD_1
	v_cvt_f32_f16_e32 v172, v170
	v_cvt_f32_f16_sdwa v173, v170 dst_sel:DWORD dst_unused:UNUSED_PAD src0_sel:WORD_1
	v_cvt_f32_f16_e32 v170, v177
	v_cvt_f32_f16_sdwa v171, v177 dst_sel:DWORD dst_unused:UNUSED_PAD src0_sel:WORD_1
	v_cvt_f32_f16_e32 v188, v175
	v_cvt_f32_f16_sdwa v189, v175 dst_sel:DWORD dst_unused:UNUSED_PAD src0_sel:WORD_1
	v_cvt_f32_f16_e32 v190, v176
	v_cvt_f32_f16_sdwa v191, v176 dst_sel:DWORD dst_unused:UNUSED_PAD src0_sel:WORD_1
	v_cvt_f32_f16_e32 v176, v174
	v_cvt_f32_f16_sdwa v177, v174 dst_sel:DWORD dst_unused:UNUSED_PAD src0_sel:WORD_1
	v_pk_fma_f32 v[124:125], v[124:125], 0.5, v[172:173] op_sel_hi:[1,0,1]
	v_pk_fma_f32 v[172:173], v[120:121], 0.5, v[186:187] op_sel_hi:[1,0,1]
	v_pk_fma_f32 v[126:127], v[126:127], 0.5, v[184:185] op_sel_hi:[1,0,1]
	v_pk_fma_f32 v[122:123], v[122:123], 0.5, v[182:183] op_sel_hi:[1,0,1]
	v_cvt_pk_f16_f32 v120, v172, v173
	v_cvt_pk_f16_f32 v121, v122, v123
	v_pk_mul_f32 v[174:175], v[124:125], v[124:125]
	v_pk_mul_f32 v[182:183], v[126:127], v[126:127]
	v_pk_fma_f32 v[174:175], v[172:173], v[172:173], v[174:175]
	v_pk_fma_f32 v[182:183], v[122:123], v[122:123], v[182:183]
	v_pk_fma_f32 v[176:177], v[116:117], 0.5, v[176:177] op_sel_hi:[1,0,1]
	v_pk_fma_f32 v[116:117], v[112:113], 0.5, v[190:191] op_sel_hi:[1,0,1]
	v_pk_fma_f32 v[184:185], v[118:119], 0.5, v[188:189] op_sel_hi:[1,0,1]
	v_pk_fma_f32 v[112:113], v[114:115], 0.5, v[170:171] op_sel_hi:[1,0,1]
	v_pk_fma_f32 v[174:175], v[176:177], v[176:177], v[174:175]
	v_pk_fma_f32 v[182:183], v[184:185], v[184:185], v[182:183]
	v_pk_fma_f32 v[174:175], v[116:117], v[116:117], v[174:175]
	v_pk_fma_f32 v[182:183], v[112:113], v[112:113], v[182:183]
	v_pk_add_f32 v[174:175], v[174:175], v[182:183]
	v_add_f32_e32 v114, v174, v175
	v_mov_b32_e32 v115, v114
	s_nop 1
	v_permlane16_swap_b32_e32 v114, v115
	v_cndmask_b32_e32 v169, v165, v169, vcc
	v_cvt_pk_f16_f32 v119, v126, v127
	v_cvt_pk_f16_f32 v118, v124, v125
	global_store_dwordx4 v[178:179], v[118:121], off
	s_nop 1
	v_cvt_pk_f16_f32 v119, v112, v113
	s_waitcnt lgkmcnt(0)
	v_add_f32_e32 v113, v114, v115
	v_lshlrev_b32_e32 v112, 2, v169
	v_mov_b32_e32 v114, v113
	s_nop 1
	v_permlane32_swap_b32_e32 v113, v114
	v_cvt_pk_f16_f32 v118, v116, v117
	v_cvt_pk_f16_f32 v117, v184, v185
	v_cvt_pk_f16_f32 v116, v176, v177
	global_store_dwordx4 v[180:181], v[116:119], off
	s_and_saveexec_b64 s[16:17], s[4:5]
	s_cbranch_execz .LBB0_300
	v_lshl_add_u32 v136, v167, 4, s18
	s_waitcnt lgkmcnt(0)
	v_add_f32_e32 v113, v113, v114
	v_lshl_add_u64 v[114:115], v[136:137], 2, s[42:43]
	global_store_dword v[114:115], v113, off

; #define PG8_WAIT_V(n) asm volatile("s_waitcnt vmcnt(" #n ")" ::: "memory")
; template <class Epi, class Sched, bool ALIGN_EPI = false, bool SP2 = false, bool F16 = false, bool TOKPERM = false>
; __device__ __forceinline__ void gemm_phase(PG8_LAS unsigned char* lds, const Gemm g, const Sched& S, const Epi& E, int wv) {
;     ...
;     for (int i = 0; i < 2; ++i) { int R, C; stage_rc(tid * 16 + i * 8192, R, C); const int Rb = Epi::PERM ? ((R & ~31) + perm32(R & 31)) : R;
;         const int Ra = TOKPERM ? ((R & ~63) + 4 * (R & 15) + ((R >> 4) & 3)) : R;
;         voffA[i] = (unsigned)(Ra * K + C) * 2u; voffB[i] = (unsigned)(Rb * K + C) * 2u; }
;     const size_t kstep = (size_t)(BK * 2);
;     const size_t hstep = (size_t)HALF * K * 2;
;     const size_t tstep = 2 * hstep;
;     const unsigned ldsw = (unsigned)wid * 1024u;
;     const int aoff = lds_byte(wr * 64 + fr, fq * 8), boff = lds_byte(wc * 32 + fr, fq * 8);
;     ...
;     Unit cur, nxt; int ui = 0;
;     if (!S.next(0, cur)) return;
;     f32x4 acc[2][2][4][2];
; #pragma unroll
;     for (int a = 0; a < 2; ++a)
; #pragma unroll
;         for (int b = 0; b < 2; ++b)
; #pragma unroll
;             for (int m = 0; m < 4; ++m)
; #pragma unroll
;                 for (int n = 0; n < 2; ++n) acc[a][b][m][n] = (f32x4){0.f, 0.f, 0.f, 0.f};
;     bf16x8 At[4][2], B0[2][2], B1[2][2];
;     const char* cA = (const char*)g.A + (size_t)cur.pm * tstep; const char* cB = (const char*)g.Bt + (size_t)cur.pn * tstep;
;     S.a_ready(cur);
;     if constexpr (SP2) {
;         PG8_STAGE(PG8_SB(0, 0), cB, voffB); PG8_STAGE(PG8_SB(0, 1), cB + hstep, voffB); PG8_STAGE(PG8_SA(0, 0), cA, voffA); PG8_STAGE(PG8_SA(0, 1), cA + hstep, voffA);
;         if (wr == 1) PG8_BAR;
;         PG8_WAIT_V(2); PG8_BAR;
;         PG8_STAGE(PG8_SB(1, 0), cB + kstep, voffB); PG8_STAGE(PG8_SA(1, 0), cA + kstep, voffA); PG8_STAGE(PG8_SB(1, 1), cB + hstep + kstep, voffB);
;         PG8_WAIT_V(6); PG8_BAR;
;     } else {
;         PG8_STAGE(PG8_SB(0, 0), cB, voffB); PG8_STAGE(PG8_SA(0, 0), cA, voffA); PG8_STAGE(PG8_SB(0, 1), cB + hstep, voffB); PG8_STAGE(PG8_SA(0, 1), cA + hstep, voffA);
;         if (wr == 1) PG8_BAR;
;         PG8_WAIT_V(4); PG8_BAR;
;         PG8_STAGE(PG8_SB(1, 0), cB + kstep, voffB); PG8_STAGE(PG8_SA(1, 0), cA + kstep, voffA); PG8_STAGE(PG8_SB(1, 1), cB + hstep + kstep, voffB);
;         PG8_WAIT_V(6); PG8_BAR;
;     }
.LBB0_676:
	s_add_i32 s37, s1, 0x18000
	s_mov_b64 s[8:9], 0x80
	s_and_b32 s36, s4, 3
	v_lshl_add_u64 v[6:7], v[6:7], 0, s[8:9]
	s_mov_b32 m0, s37
	s_add_i32 s44, s1, 0x1a000
	s_lshl_b32 s4, s5, 13
	s_lshl_b32 s10, s36, 12
	s_waitcnt vmcnt(2)
	s_barrier
	global_load_lds_dwordx4 v[6:7], off
	v_lshl_add_u64 v[4:5], v[4:5], 0, s[8:9]
	s_mov_b32 m0, s44
	s_add_i32 s45, s1, 0x8000
	s_add_i32 s51, s1, 0xa000
	global_load_lds_dwordx4 v[4:5], off
	v_lshl_add_u64 v[2:3], v[2:3], 0, s[8:9]
	s_mov_b32 m0, s45
	s_add_u32 s6, s54, 0x40080
	global_load_lds_dwordx4 v[2:3], off
	v_lshl_add_u64 v[0:1], v[0:1], 0, s[8:9]
	s_mov_b32 m0, s51
	s_addc_u32 s7, s55, 0
	s_add_i32 s58, s1, 0x1c000
	global_load_lds_dwordx4 v[0:1], off
	v_lshl_add_u64 v[0:1], s[6:7], 0, v[130:131]
	s_mov_b32 m0, s58
	s_add_i32 s59, s1, 0x1e000
	global_load_lds_dwordx4 v[0:1], off
	v_lshl_add_u64 v[0:1], s[6:7], 0, v[134:135]
	s_mov_b32 m0, s59
	s_mov_b32 s60, 0
	global_load_lds_dwordx4 v[0:1], off
	v_bfe_u32 v0, v8, 4, 2
	v_and_b32_e32 v1, 15, v8
	v_lshlrev_b32_e32 v3, 4, v0
	v_lshl_or_b32 v146, s5, 6, v1
	v_lshl_or_b32 v1, v1, 6, v3
	v_lshlrev_b32_e32 v3, 2, v8
	v_and_b32_e32 v3, 32, v3
	v_lshlrev_b32_e32 v2, 3, v0
	v_bitop3_b32 v147, v1, s4, v3 bitop3:0xde
	v_cmp_eq_u32_e64 s[4:5], 0, v0
	v_lshlrev_b32_e32 v0, 14, v9
	v_and_b32_e32 v0, 0xffff8000, v0
	v_lshl_or_b32 v148, s36, 5, v2
	v_lshl_add_u32 v0, v10, 11, v0
	v_and_b32_e32 v2, 1, v9
	v_lshl_or_b32 v0, v2, 6, v0
	v_lshl_add_u32 v138, v11, 1, v0
	v_lshlrev_b32_e32 v0, 14, v12
	v_and_b32_e32 v0, 0xffff8000, v0
	s_waitcnt vmcnt(6)
	v_lshl_add_u32 v0, v13, 11, v0
	v_and_b32_e32 v2, 1, v12
	v_bitop3_b32 v1, v1, s10, v3 bitop3:0xde
	v_lshl_or_b32 v0, v2, 6, v0
	s_ashr_i32 s61, s28, 31
	s_mov_b32 s62, s28
	s_ashr_i32 s63, s26, 31
	v_mov_b32_e32 v139, v137
	v_lshl_add_u32 v140, v14, 1, v0
	v_mov_b32_e32 v141, v137
	v_mov_b64_e32 v[142:143], 0x100
	v_mov_b64_e32 v[144:145], 0xff
	v_or_b32_e32 v149, 0x10000, v1
	v_add_u32_e32 v150, 0x10400, v1
	v_add_u32_e32 v151, 0x10800, v1
	v_add_u32_e32 v152, 0x10c00, v1
	v_or_b32_e32 v153, 0x14000, v1
	v_add_u32_e32 v154, 0x14400, v1
	v_add_u32_e32 v155, 0x14800, v1
	v_add_u32_e32 v156, 0x14c00, v1
	s_add_i32 s64, s1, 0xc000
	s_add_i32 s65, s1, 0xe000
	v_or_b32_e32 v157, 0x18000, v1
	v_add_u32_e32 v158, 0x18400, v1
	v_add_u32_e32 v159, 0x18800, v1
	v_add_u32_e32 v160, 0x18c00, v1
	v_or_b32_e32 v161, 0x1c000, v1
	v_add_u32_e32 v162, 0x1c400, v1
	v_add_u32_e32 v163, 0x1c800, v1
	v_add_u32_e32 v164, 0x1cc00, v1
	v_mbcnt_hi_u32_b32 v165, -1, v226
	s_barrier
	s_mov_b32 s99, 0
	s_branch .LBB0_678

; #define PG8_STAGE(bufoff, gbase, voff) do { _Pragma("unroll") for (int _i = 0; _i < 2; ++_i) \
;         __builtin_amdgcn_global_load_lds((const unsigned*)((const char*)(gbase) + (voff)[_i]), (PG8_LAS unsigned*)(lds + (bufoff) + ldsw + _i * 8192), 16, 0, 0); } while (0)
; #define PG8_LDA(dst, b, h) do { _Pragma("unroll") for (int m = 0; m < 4; ++m) _Pragma("unroll") for (int k = 0; k < 2; ++k) dst[m][k] = *(const PG8_LAS bf16x8*)(lds + PG8_SA(b, h) + aoff + m * 2048 + k * 1024); } while (0)
; #define PG8_LDB(dst, b, h) do { _Pragma("unroll") for (int n = 0; n < 2; ++n) _Pragma("unroll") for (int k = 0; k < 2; ++k) dst[n][k] = *(const PG8_LAS bf16x8*)(lds + PG8_SB(b, h) + boff + n * 2048 + k * 1024); } while (0)
; #define PG8_MMA(ai, bj, At, Bt) do { __builtin_amdgcn_s_setprio(1); _Pragma("unroll") for (int m = 0; m < 4; ++m) _Pragma("unroll") for (int n = 0; n < 2; ++n) _Pragma("unroll") for (int k = 0; k < 2; ++k) \
;         acc[ai][bj][m][n] = mma16<F16>(Bt[n][k], At[m][k], acc[ai][bj][m][n]); __builtin_amdgcn_s_setprio(0); } while (0)
; #define PG8_WAIT_V(n) asm volatile("s_waitcnt vmcnt(" #n ")" ::: "memory")
; #define PG8_WAIT_L(n) asm volatile("s_waitcnt lgkmcnt(" #n ")" ::: "memory")
; #define PG8_BAR __builtin_amdgcn_s_barrier()
; #define PG8_SCHED __builtin_amdgcn_sched_barrier(0)
; template <class Epi, class Sched, bool ALIGN_EPI = false, bool SP2 = false, bool F16 = false, bool TOKPERM = false>
; __device__ __forceinline__ void gemm_phase(PG8_LAS unsigned char* lds, const Gemm g, const Sched& S, const Epi& E, int wv) {
;     ...
;             PG8_LDB(B0, 0, 0); PG8_LDB(B1, 0, 1); PG8_SCHED; PG8_LDA(At, 0, 0); PG8_STAGE(PG8_SA(1, 1), a1 + hstep, voffA);
;             PG8_WAIT_V(8); PG8_WAIT_L(0); PG8_BAR; PG8_MMA(0, 0, At, B0); PG8_MMA(0, 1, At, B1); PG8_BAR; PG8_SCHED;
;             PG8_LDA(At, 0, 1); PG8_STAGE(PG8_SB(0, 0), b2, voffB); PG8_STAGE(PG8_SB(0, 1), b2 + hstep, voffB); PG8_STAGE(PG8_SA(0, 0), a2, voffA);
;             PG8_WAIT_V(8); PG8_WAIT_L(0); PG8_BAR; PG8_MMA(1, 0, At, B0); PG8_MMA(1, 1, At, B1); PG8_BAR; PG8_SCHED;
.LBB0_685:
	ds_read_b128 v[166:169], v149
	ds_read_b128 v[170:173], v150
	ds_read_b128 v[174:177], v151
	ds_read_b128 v[178:181], v152
	ds_read_b128 v[182:185], v153
	ds_read_b128 v[186:189], v154
	ds_read_b128 v[190:193], v155
	ds_read_b128 v[194:197], v156
	s_add_u32 s54, s52, 0xfffc0080
	s_addc_u32 s55, s53, -1
	s_cmp_eq_u32 s69, 12
	s_cselect_b32 s57, s13, s55
	s_cselect_b32 s56, s49, s54
	s_cselect_b32 s55, s11, s68
	s_cselect_b32 s54, s66, s67
	s_mov_b32 m0, s64
	v_lshl_add_u64 v[232:233], s[52:53], 0, v[138:139]
	ds_read_b128 v[198:201], v147
	ds_read_b128 v[202:205], v147 offset:1024
	ds_read_b128 v[206:209], v147 offset:2048
	ds_read_b128 v[210:213], v147 offset:3072
	ds_read_b128 v[214:217], v147 offset:4096
	ds_read_b128 v[218:221], v147 offset:5120
	ds_read_b128 v[222:225], v147 offset:6144
	ds_read_b128 v[228:231], v147 offset:7168
	global_load_lds_dwordx4 v[232:233], off
	v_lshl_add_u64 v[232:233], s[52:53], 0, v[140:141]
	s_mov_b32 m0, s65
	s_nop 0
	global_load_lds_dwordx4 v[232:233], off
	s_waitcnt vmcnt(24)
	s_cmp_eq_u32 s99, 1
	s_cbranch_scc1 .Lvmw_685_0
	s_waitcnt vmcnt(8)
.Lvmw_685_0:
	s_waitcnt lgkmcnt(0)
	s_barrier
	s_setprio 1
	s_waitcnt lgkmcnt(0)
	v_mfma_f32_16x16x32_bf16 v[124:127], v[166:169], v[198:201], v[124:127]
	v_mfma_f32_16x16x32_bf16 v[120:123], v[174:177], v[198:201], v[120:123]
	v_mfma_f32_16x16x32_bf16 v[108:111], v[166:169], v[206:209], v[108:111]
	v_mfma_f32_16x16x32_bf16 v[104:107], v[174:177], v[206:209], v[104:107]
	v_mfma_f32_16x16x32_bf16 v[92:95], v[166:169], v[214:217], v[92:95]
	v_mfma_f32_16x16x32_bf16 v[88:91], v[174:177], v[214:217], v[88:91]
	v_mfma_f32_16x16x32_bf16 v[76:79], v[166:169], v[222:225], v[76:79]
	v_mfma_f32_16x16x32_bf16 v[72:75], v[174:177], v[222:225], v[72:75]
	v_mfma_f32_16x16x32_bf16 v[124:127], v[170:173], v[202:205], v[124:127]
	v_mfma_f32_16x16x32_bf16 v[120:123], v[178:181], v[202:205], v[120:123]
	v_mfma_f32_16x16x32_bf16 v[108:111], v[170:173], v[210:213], v[108:111]
	v_mfma_f32_16x16x32_bf16 v[104:107], v[178:181], v[210:213], v[104:107]
	v_mfma_f32_16x16x32_bf16 v[92:95], v[170:173], v[218:221], v[92:95]
	v_mfma_f32_16x16x32_bf16 v[88:91], v[178:181], v[218:221], v[88:91]
	v_mfma_f32_16x16x32_bf16 v[76:79], v[170:173], v[228:231], v[76:79]
	v_mfma_f32_16x16x32_bf16 v[72:75], v[178:181], v[228:231], v[72:75]
	s_setprio 0
	s_setprio 1
	v_mfma_f32_16x16x32_bf16 v[116:119], v[182:185], v[198:201], v[116:119]
	v_mfma_f32_16x16x32_bf16 v[112:115], v[190:193], v[198:201], v[112:115]
	v_mfma_f32_16x16x32_bf16 v[100:103], v[182:185], v[206:209], v[100:103]
	v_mfma_f32_16x16x32_bf16 v[96:99], v[190:193], v[206:209], v[96:99]
	v_mfma_f32_16x16x32_bf16 v[84:87], v[182:185], v[214:217], v[84:87]
	v_mfma_f32_16x16x32_bf16 v[80:83], v[190:193], v[214:217], v[80:83]
	v_mfma_f32_16x16x32_bf16 v[68:71], v[182:185], v[222:225], v[68:71]
	v_mfma_f32_16x16x32_bf16 v[64:67], v[190:193], v[222:225], v[64:67]
	v_mfma_f32_16x16x32_bf16 v[116:119], v[186:189], v[202:205], v[116:119]
	v_mfma_f32_16x16x32_bf16 v[112:115], v[194:197], v[202:205], v[112:115]
	v_mfma_f32_16x16x32_bf16 v[100:103], v[186:189], v[210:213], v[100:103]
	v_mfma_f32_16x16x32_bf16 v[96:99], v[194:197], v[210:213], v[96:99]
	v_mfma_f32_16x16x32_bf16 v[84:87], v[186:189], v[218:221], v[84:87]
	v_mfma_f32_16x16x32_bf16 v[80:83], v[194:197], v[218:221], v[80:83]
	v_mfma_f32_16x16x32_bf16 v[68:71], v[186:189], v[228:231], v[68:71]
	v_mfma_f32_16x16x32_bf16 v[64:67], v[194:197], v[228:231], v[64:67]
	s_setprio 0
	s_barrier
	s_mov_b32 m0, s2
	v_lshl_add_u64 v[232:233], s[54:55], 0, v[130:131]
	s_add_u32 s70, s54, 0x40000
	ds_read_b128 v[198:201], v147 offset:16384
	ds_read_b128 v[202:205], v147 offset:17408
	ds_read_b128 v[206:209], v147 offset:18432
	ds_read_b128 v[210:213], v147 offset:19456
	ds_read_b128 v[214:217], v147 offset:20480
	ds_read_b128 v[218:221], v147 offset:21504
	ds_read_b128 v[222:225], v147 offset:22528
	ds_read_b128 v[228:231], v147 offset:23552
	global_load_lds_dwordx4 v[232:233], off
	v_lshl_add_u64 v[234:235], s[54:55], 0, v[134:135]
	s_mov_b32 m0, s3
	s_addc_u32 s71, s55, 0
	global_load_lds_dwordx4 v[234:235], off
	v_lshl_add_u64 v[236:237], s[70:71], 0, v[130:131]
	s_mov_b32 m0, s20
	v_lshl_add_u64 v[238:239], s[56:57], 0, v[132:133]
	global_load_lds_dwordx4 v[236:237], off
	v_lshl_add_u64 v[236:237], s[70:71], 0, v[134:135]
	s_mov_b32 m0, s21
	s_nop 0
	global_load_lds_dwordx4 v[236:237], off
	v_lshl_add_u64 v[236:237], s[56:57], 0, v[128:129]
	s_mov_b32 m0, s1
	s_nop 0
	global_load_lds_dwordx4 v[236:237], off
	s_mov_b32 m0, s22
	s_nop 0
	global_load_lds_dwordx4 v[238:239], off
	s_waitcnt vmcnt(24)
	s_cmp_eq_u32 s99, 1
	s_cbranch_scc1 .Lvmw_685_1
	s_waitcnt vmcnt(8)
; #define PG8_STAGE(bufoff, gbase, voff) do { _Pragma("unroll") for (int _i = 0; _i < 2; ++_i) \
;         __builtin_amdgcn_global_load_lds((const unsigned*)((const char*)(gbase) + (voff)[_i]), (PG8_LAS unsigned*)(lds + (bufoff) + ldsw + _i * 8192), 16, 0, 0); } while (0)
; #define PG8_LDA(dst, b, h) do { _Pragma("unroll") for (int m = 0; m < 4; ++m) _Pragma("unroll") for (int k = 0; k < 2; ++k) dst[m][k] = *(const PG8_LAS bf16x8*)(lds + PG8_SA(b, h) + aoff + m * 2048 + k * 1024); } while (0)
; #define PG8_LDB(dst, b, h) do { _Pragma("unroll") for (int n = 0; n < 2; ++n) _Pragma("unroll") for (int k = 0; k < 2; ++k) dst[n][k] = *(const PG8_LAS bf16x8*)(lds + PG8_SB(b, h) + boff + n * 2048 + k * 1024); } while (0)
; #define PG8_MMA(ai, bj, At, Bt) do { __builtin_amdgcn_s_setprio(1); _Pragma("unroll") for (int m = 0; m < 4; ++m) _Pragma("unroll") for (int n = 0; n < 2; ++n) _Pragma("unroll") for (int k = 0; k < 2; ++k) \
;         acc[ai][bj][m][n] = mma16<F16>(Bt[n][k], At[m][k], acc[ai][bj][m][n]); __builtin_amdgcn_s_setprio(0); } while (0)
; #define PG8_WAIT_V(n) asm volatile("s_waitcnt vmcnt(" #n ")" ::: "memory")
; #define PG8_WAIT_L(n) asm volatile("s_waitcnt lgkmcnt(" #n ")" ::: "memory")
; #define PG8_BAR __builtin_amdgcn_s_barrier()
; #define PG8_SCHED __builtin_amdgcn_sched_barrier(0)
; template <class Epi, class Sched, bool ALIGN_EPI = false, bool SP2 = false, bool F16 = false, bool TOKPERM = false>
; __device__ __forceinline__ void gemm_phase(PG8_LAS unsigned char* lds, const Gemm g, const Sched& S, const Epi& E, int wv) {
;     ...
;             PG8_WAIT_V(8); PG8_WAIT_L(0); PG8_BAR; PG8_MMA(1, 0, At, B0); PG8_MMA(1, 1, At, B1); PG8_BAR; PG8_SCHED;
;             PG8_LDB(B0, 1, 0); PG8_LDB(B1, 1, 1); PG8_SCHED; PG8_LDA(At, 1, 0); PG8_STAGE(PG8_SA(0, 1), a2 + hstep, voffA);
;             PG8_WAIT_V(8); PG8_WAIT_L(0); PG8_BAR; PG8_MMA(0, 0, At, B0); PG8_MMA(0, 1, At, B1); PG8_BAR; PG8_SCHED;
.Lvmw_685_1:
	s_mov_b32 s99, 0
	s_waitcnt lgkmcnt(0)
	s_barrier
	s_setprio 1
	s_waitcnt lgkmcnt(0)
	v_mfma_f32_16x16x32_bf16 v[60:63], v[166:169], v[198:201], v[60:63]
	v_mfma_f32_16x16x32_bf16 v[56:59], v[174:177], v[198:201], v[56:59]
	v_mfma_f32_16x16x32_bf16 v[44:47], v[166:169], v[206:209], v[44:47]
	v_mfma_f32_16x16x32_bf16 v[40:43], v[174:177], v[206:209], v[40:43]
	v_mfma_f32_16x16x32_bf16 v[28:31], v[166:169], v[214:217], v[28:31]
	v_mfma_f32_16x16x32_bf16 v[24:27], v[174:177], v[214:217], v[24:27]
	v_mfma_f32_16x16x32_bf16 v[12:15], v[166:169], v[222:225], v[12:15]
	v_mfma_f32_16x16x32_bf16 v[8:11], v[174:177], v[222:225], v[8:11]
	v_mfma_f32_16x16x32_bf16 v[60:63], v[170:173], v[202:205], v[60:63]
	v_mfma_f32_16x16x32_bf16 v[56:59], v[178:181], v[202:205], v[56:59]
	v_mfma_f32_16x16x32_bf16 v[44:47], v[170:173], v[210:213], v[44:47]
	v_mfma_f32_16x16x32_bf16 v[40:43], v[178:181], v[210:213], v[40:43]
	v_mfma_f32_16x16x32_bf16 v[28:31], v[170:173], v[218:221], v[28:31]
	v_mfma_f32_16x16x32_bf16 v[24:27], v[178:181], v[218:221], v[24:27]
	v_mfma_f32_16x16x32_bf16 v[12:15], v[170:173], v[228:231], v[12:15]
	v_mfma_f32_16x16x32_bf16 v[8:11], v[178:181], v[228:231], v[8:11]
	s_setprio 0
	s_setprio 1
	v_mfma_f32_16x16x32_bf16 v[52:55], v[182:185], v[198:201], v[52:55]
	v_mfma_f32_16x16x32_bf16 v[48:51], v[190:193], v[198:201], v[48:51]
	v_mfma_f32_16x16x32_bf16 v[36:39], v[182:185], v[206:209], v[36:39]
	v_mfma_f32_16x16x32_bf16 v[32:35], v[190:193], v[206:209], v[32:35]
	v_mfma_f32_16x16x32_bf16 v[20:23], v[182:185], v[214:217], v[20:23]
	v_mfma_f32_16x16x32_bf16 v[16:19], v[190:193], v[214:217], v[16:19]
	v_mfma_f32_16x16x32_bf16 v[4:7], v[182:185], v[222:225], v[4:7]
	v_mfma_f32_16x16x32_bf16 v[0:3], v[190:193], v[222:225], v[0:3]
	v_mfma_f32_16x16x32_bf16 v[52:55], v[186:189], v[202:205], v[52:55]
	v_mfma_f32_16x16x32_bf16 v[48:51], v[194:197], v[202:205], v[48:51]
	v_mfma_f32_16x16x32_bf16 v[36:39], v[186:189], v[210:213], v[36:39]
	v_mfma_f32_16x16x32_bf16 v[32:35], v[194:197], v[210:213], v[32:35]
	v_mfma_f32_16x16x32_bf16 v[20:23], v[186:189], v[218:221], v[20:23]
	v_mfma_f32_16x16x32_bf16 v[16:19], v[194:197], v[218:221], v[16:19]
	v_mfma_f32_16x16x32_bf16 v[4:7], v[186:189], v[228:231], v[4:7]
	v_mfma_f32_16x16x32_bf16 v[0:3], v[194:197], v[228:231], v[0:3]
	s_setprio 0
	s_barrier
	ds_read_b128 v[166:169], v157
	ds_read_b128 v[170:173], v158
	ds_read_b128 v[174:177], v159
	ds_read_b128 v[178:181], v160
	ds_read_b128 v[182:185], v161
	ds_read_b128 v[186:189], v162
	ds_read_b128 v[190:193], v163
	ds_read_b128 v[194:197], v164
	s_add_u32 s56, s56, 0x40000
	s_addc_u32 s57, s57, 0
	s_mov_b32 m0, s23
	v_lshl_add_u64 v[240:241], s[56:57], 0, v[128:129]
	ds_read_b128 v[198:201], v147 offset:32768
	ds_read_b128 v[202:205], v147 offset:33792
	ds_read_b128 v[206:209], v147 offset:34816
	ds_read_b128 v[210:213], v147 offset:35840
	ds_read_b128 v[214:217], v147 offset:36864
	ds_read_b128 v[218:221], v147 offset:37888
	ds_read_b128 v[222:225], v147 offset:38912
	ds_read_b128 v[228:231], v147 offset:39936
	global_load_lds_dwordx4 v[240:241], off
	v_lshl_add_u64 v[240:241], s[56:57], 0, v[132:133]
	s_mov_b32 m0, s33
	s_nop 0
	global_load_lds_dwordx4 v[240:241], off
	s_waitcnt vmcnt(8)
	s_waitcnt lgkmcnt(0)
	s_barrier
	s_setprio 1
	s_waitcnt lgkmcnt(0)
	v_mfma_f32_16x16x32_bf16 v[124:127], v[166:169], v[198:201], v[124:127]
	v_mfma_f32_16x16x32_bf16 v[120:123], v[174:177], v[198:201], v[120:123]
	v_mfma_f32_16x16x32_bf16 v[108:111], v[166:169], v[206:209], v[108:111]
	v_mfma_f32_16x16x32_bf16 v[104:107], v[174:177], v[206:209], v[104:107]
	v_mfma_f32_16x16x32_bf16 v[92:95], v[166:169], v[214:217], v[92:95]
	v_mfma_f32_16x16x32_bf16 v[88:91], v[174:177], v[214:217], v[88:91]
	v_mfma_f32_16x16x32_bf16 v[76:79], v[166:169], v[222:225], v[76:79]
	v_mfma_f32_16x16x32_bf16 v[72:75], v[174:177], v[222:225], v[72:75]
	v_mfma_f32_16x16x32_bf16 v[124:127], v[170:173], v[202:205], v[124:127]
	v_mfma_f32_16x16x32_bf16 v[120:123], v[178:181], v[202:205], v[120:123]
	v_mfma_f32_16x16x32_bf16 v[108:111], v[170:173], v[210:213], v[108:111]
	v_mfma_f32_16x16x32_bf16 v[104:107], v[178:181], v[210:213], v[104:107]
	v_mfma_f32_16x16x32_bf16 v[92:95], v[170:173], v[218:221], v[92:95]
	v_mfma_f32_16x16x32_bf16 v[88:91], v[178:181], v[218:221], v[88:91]
	v_mfma_f32_16x16x32_bf16 v[76:79], v[170:173], v[228:231], v[76:79]
	v_mfma_f32_16x16x32_bf16 v[72:75], v[178:181], v[228:231], v[72:75]
	s_setprio 0
	s_setprio 1
	v_mfma_f32_16x16x32_bf16 v[116:119], v[182:185], v[198:201], v[116:119]
	v_mfma_f32_16x16x32_bf16 v[112:115], v[190:193], v[198:201], v[112:115]
	v_mfma_f32_16x16x32_bf16 v[100:103], v[182:185], v[206:209], v[100:103]
	v_mfma_f32_16x16x32_bf16 v[96:99], v[190:193], v[206:209], v[96:99]
	v_mfma_f32_16x16x32_bf16 v[84:87], v[182:185], v[214:217], v[84:87]
	v_mfma_f32_16x16x32_bf16 v[80:83], v[190:193], v[214:217], v[80:83]
	v_mfma_f32_16x16x32_bf16 v[68:71], v[182:185], v[222:225], v[68:71]
	v_mfma_f32_16x16x32_bf16 v[64:67], v[190:193], v[222:225], v[64:67]
	v_mfma_f32_16x16x32_bf16 v[116:119], v[186:189], v[202:205], v[116:119]
	v_mfma_f32_16x16x32_bf16 v[112:115], v[194:197], v[202:205], v[112:115]
	v_mfma_f32_16x16x32_bf16 v[100:103], v[186:189], v[210:213], v[100:103]
	v_mfma_f32_16x16x32_bf16 v[96:99], v[194:197], v[210:213], v[96:99]
	v_mfma_f32_16x16x32_bf16 v[84:87], v[186:189], v[218:221], v[84:87]
	v_mfma_f32_16x16x32_bf16 v[80:83], v[194:197], v[218:221], v[80:83]
	v_mfma_f32_16x16x32_bf16 v[68:71], v[186:189], v[228:231], v[68:71]
	v_mfma_f32_16x16x32_bf16 v[64:67], v[194:197], v[228:231], v[64:67]
	s_setprio 0
	s_barrier
; #define PG8_STAGE(bufoff, gbase, voff) do { _Pragma("unroll") for (int _i = 0; _i < 2; ++_i) \
;         __builtin_amdgcn_global_load_lds((const unsigned*)((const char*)(gbase) + (voff)[_i]), (PG8_LAS unsigned*)(lds + (bufoff) + ldsw + _i * 8192), 16, 0, 0); } while (0)
; #define PG8_LDA(dst, b, h) do { _Pragma("unroll") for (int m = 0; m < 4; ++m) _Pragma("unroll") for (int k = 0; k < 2; ++k) dst[m][k] = *(const PG8_LAS bf16x8*)(lds + PG8_SA(b, h) + aoff + m * 2048 + k * 1024); } while (0)
; #define PG8_MMA(ai, bj, At, Bt) do { __builtin_amdgcn_s_setprio(1); _Pragma("unroll") for (int m = 0; m < 4; ++m) _Pragma("unroll") for (int n = 0; n < 2; ++n) _Pragma("unroll") for (int k = 0; k < 2; ++k) \
;         acc[ai][bj][m][n] = mma16<F16>(Bt[n][k], At[m][k], acc[ai][bj][m][n]); __builtin_amdgcn_s_setprio(0); } while (0)
; #define PG8_WAIT_V(n) asm volatile("s_waitcnt vmcnt(" #n ")" ::: "memory")
; #define PG8_WAIT_L(n) asm volatile("s_waitcnt lgkmcnt(" #n ")" ::: "memory")
; #define PG8_BAR __builtin_amdgcn_s_barrier()
; #define PG8_SCHED __builtin_amdgcn_sched_barrier(0)
; template <class Epi, class Sched, bool ALIGN_EPI = false, bool SP2 = false, bool F16 = false, bool TOKPERM = false>
; __device__ __forceinline__ void gemm_phase(PG8_LAS unsigned char* lds, const Gemm g, const Sched& S, const Epi& E, int wv) {
;     ...
;             PG8_LDA(At, 1, 1); PG8_STAGE(PG8_SB(1, 0), b3, voffB); PG8_STAGE(PG8_SB(1, 1), b3 + hstep, voffB); PG8_STAGE(PG8_SA(1, 0), a3, voffA);
;             PG8_WAIT_V(8); PG8_WAIT_L(0); PG8_BAR; PG8_MMA(1, 0, At, B0); PG8_MMA(1, 1, At, B1); PG8_BAR; PG8_SCHED;
	s_mov_b32 m0, s37
	v_lshl_add_u64 v[232:233], v[232:233], 0, s[8:9]
	s_add_u32 s54, s54, 0x40080
	ds_read_b128 v[198:201], v147 offset:49152
	ds_read_b128 v[202:205], v147 offset:50176
	ds_read_b128 v[206:209], v147 offset:51200
	ds_read_b128 v[210:213], v147 offset:52224
	ds_read_b128 v[214:217], v147 offset:53248
	ds_read_b128 v[218:221], v147 offset:54272
	ds_read_b128 v[222:225], v147 offset:55296
	ds_read_b128 v[228:231], v147 offset:56320
	global_load_lds_dwordx4 v[232:233], off
	v_lshl_add_u64 v[232:233], v[234:235], 0, s[8:9]
	s_mov_b32 m0, s44
	s_addc_u32 s55, s55, 0
	global_load_lds_dwordx4 v[232:233], off
	v_lshl_add_u64 v[232:233], s[54:55], 0, v[130:131]
	s_mov_b32 m0, s58
	s_nop 0
	global_load_lds_dwordx4 v[232:233], off
	v_lshl_add_u64 v[232:233], s[54:55], 0, v[134:135]
	s_mov_b32 m0, s59
	s_nop 0
	global_load_lds_dwordx4 v[232:233], off
	v_lshl_add_u64 v[232:233], v[236:237], 0, s[8:9]
	s_mov_b32 m0, s45
	s_nop 0
	global_load_lds_dwordx4 v[232:233], off
	v_lshl_add_u64 v[232:233], v[238:239], 0, s[8:9]
	s_mov_b32 m0, s51
	s_nop 0
	global_load_lds_dwordx4 v[232:233], off
	s_waitcnt vmcnt(8)
	s_waitcnt lgkmcnt(0)
	s_barrier
	s_setprio 1
	s_waitcnt lgkmcnt(0)
	v_mfma_f32_16x16x32_bf16 v[60:63], v[166:169], v[198:201], v[60:63]
	v_mfma_f32_16x16x32_bf16 v[56:59], v[174:177], v[198:201], v[56:59]
	v_mfma_f32_16x16x32_bf16 v[44:47], v[166:169], v[206:209], v[44:47]
	v_mfma_f32_16x16x32_bf16 v[40:43], v[174:177], v[206:209], v[40:43]
	v_mfma_f32_16x16x32_bf16 v[28:31], v[166:169], v[214:217], v[28:31]
	v_mfma_f32_16x16x32_bf16 v[24:27], v[174:177], v[214:217], v[24:27]
	v_mfma_f32_16x16x32_bf16 v[12:15], v[166:169], v[222:225], v[12:15]
	v_mfma_f32_16x16x32_bf16 v[8:11], v[174:177], v[222:225], v[8:11]
	v_mfma_f32_16x16x32_bf16 v[60:63], v[170:173], v[202:205], v[60:63]
	v_mfma_f32_16x16x32_bf16 v[56:59], v[178:181], v[202:205], v[56:59]
	v_mfma_f32_16x16x32_bf16 v[44:47], v[170:173], v[210:213], v[44:47]
	v_mfma_f32_16x16x32_bf16 v[40:43], v[178:181], v[210:213], v[40:43]
	v_mfma_f32_16x16x32_bf16 v[28:31], v[170:173], v[218:221], v[28:31]
	v_mfma_f32_16x16x32_bf16 v[24:27], v[178:181], v[218:221], v[24:27]
	v_mfma_f32_16x16x32_bf16 v[12:15], v[170:173], v[228:231], v[12:15]
	v_mfma_f32_16x16x32_bf16 v[8:11], v[178:181], v[228:231], v[8:11]
	s_setprio 0
	s_setprio 1
	v_mfma_f32_16x16x32_bf16 v[52:55], v[182:185], v[198:201], v[52:55]
	v_mfma_f32_16x16x32_bf16 v[48:51], v[190:193], v[198:201], v[48:51]
	v_mfma_f32_16x16x32_bf16 v[36:39], v[182:185], v[206:209], v[36:39]
	v_mfma_f32_16x16x32_bf16 v[32:35], v[190:193], v[206:209], v[32:35]
	v_mfma_f32_16x16x32_bf16 v[20:23], v[182:185], v[214:217], v[20:23]
	v_mfma_f32_16x16x32_bf16 v[16:19], v[190:193], v[214:217], v[16:19]
	v_mfma_f32_16x16x32_bf16 v[4:7], v[182:185], v[222:225], v[4:7]
	v_mfma_f32_16x16x32_bf16 v[0:3], v[190:193], v[222:225], v[0:3]
	v_mfma_f32_16x16x32_bf16 v[52:55], v[186:189], v[202:205], v[52:55]
	v_mfma_f32_16x16x32_bf16 v[48:51], v[194:197], v[202:205], v[48:51]
	v_mfma_f32_16x16x32_bf16 v[36:39], v[186:189], v[210:213], v[36:39]
	v_mfma_f32_16x16x32_bf16 v[32:35], v[194:197], v[210:213], v[32:35]
	v_mfma_f32_16x16x32_bf16 v[20:23], v[186:189], v[218:221], v[20:23]
	v_mfma_f32_16x16x32_bf16 v[16:19], v[194:197], v[218:221], v[16:19]
	v_mfma_f32_16x16x32_bf16 v[4:7], v[186:189], v[228:231], v[4:7]
	v_mfma_f32_16x16x32_bf16 v[0:3], v[194:197], v[228:231], v[0:3]
	s_setprio 0
	s_barrier
	s_add_i32 s69, s69, 2
	s_add_u32 s52, s52, 0x100
	s_addc_u32 s53, s53, 0
	s_add_u32 s67, s67, 0x100
	s_addc_u32 s68, s68, 0
	s_cmp_gt_u32 s69, 13
	s_cbranch_scc0 .LBB0_685
;   __device__ __forceinline__ void operator()(const pg8::f32x4 (&acc)[2][2][4][2], const pg8::Unit& u, int wr, int wc, int fr, int fq) const {
;     int z; asm volatile("v_mov_b32 %0, 0" : "=v"(z));
;     const int row0 = u.pm * 256 + wr * 64 + fr + z, colb = u.pn * 256 + wc * 32 + 8 * fq + z;
; #pragma unroll
;     for (int ai = 0; ai < 2; ++ai)
; #pragma unroll
;       for (int m = 0; m < 4; ++m) {
;         const int tok = row0 + ai * 128 + m * 16; float ss = 0.f;
; #pragma unroll
;         for (int bj = 0; bj < 2; ++bj) {
;           const unsigned off = (unsigned)tok * DM + colb + 128 * bj;
;           f8_t n = __builtin_convertvector(*(const h8_t*)(x16 + off), f8_t);
; #pragma unroll
;           for (int c = 0; c < 4; ++c) { n[c] += sc * acc[ai][bj][m][0][c]; n[4 + c] += sc * acc[ai][bj][m][1][c]; }
;           if (aux) {
;             *(h8_t*)(x16 + off) = __builtin_convertvector(n, h8_t);
;             ss += ((n[0] * n[0] + n[1] * n[1]) + (n[2] * n[2] + n[3] * n[3])) + ((n[4] * n[4] + n[5] * n[5]) + (n[6] * n[6] + n[7] * n[7]));
;           } else {
;             *(f32x4*)(xout + off) = (f32x4){n[0], n[1], n[2], n[3]}; *(f32x4*)(xout + off + 4) = (f32x4){n[4], n[5], n[6], n[7]};
;           }
;         }
;         if (aux) { ss += __shfl_xor(ss, 16); ss += __shfl_xor(ss, 32); if (fq == 0) ssq[(unsigned)tok * 16 + u.pn * 4 + wc] = ss; }
;         if (m & 1) asm volatile("" ::: "memory");
;       }
;   }
	s_mov_b32 s99, 1
	s_lshl_b32 s11, s50, 8
	v_lshl_or_b32 v166, s48, 8, v148
	v_mov_b32 v136, 0
	v_xor_b32_e32 v169, 32, v165
	v_add3_u32 v167, s11, v146, v136
	v_add_u32_e32 v168, v166, v136
	v_lshl_add_u32 v136, v167, 10, v168
	v_lshl_add_u64 v[178:179], v[136:137], 1, s[40:41]
	v_add_u32_e32 v136, 0x80, v136
	global_load_dwordx4 v[170:173], v[178:179], off
	v_lshl_add_u64 v[180:181], v[136:137], 1, s[40:41]
	global_load_dwordx4 v[174:177], v[180:181], off
	v_add_u32_e32 v136, 16, v167
	v_lshl_add_u32 v136, v136, 10, v168
	v_lshl_add_u64 v[224:225], v[136:137], 1, s[40:41]
	v_add_u32_e32 v136, 0x80, v136
	global_load_dwordx4 v[192:195], v[224:225], off
	v_lshl_add_u64 v[248:249], v[136:137], 1, s[40:41]
	global_load_dwordx4 v[196:199], v[248:249], off
	v_add_u32_e32 v136, 32, v167
	v_lshl_add_u32 v136, v136, 10, v168
	v_lshl_add_u64 v[224:225], v[136:137], 1, s[40:41]
	v_add_u32_e32 v136, 0x80, v136
	global_load_dwordx4 v[200:203], v[224:225], off
	v_lshl_add_u64 v[248:249], v[136:137], 1, s[40:41]
	global_load_dwordx4 v[204:207], v[248:249], off
	v_add_u32_e32 v136, 48, v167
	v_lshl_add_u32 v136, v136, 10, v168
	v_lshl_add_u64 v[224:225], v[136:137], 1, s[40:41]
	v_add_u32_e32 v136, 0x80, v136
	global_load_dwordx4 v[208:211], v[224:225], off
	v_lshl_add_u64 v[248:249], v[136:137], 1, s[40:41]
	global_load_dwordx4 v[212:215], v[248:249], off
	v_add_u32_e32 v136, 0x80, v167
	v_lshl_add_u32 v136, v136, 10, v168
	v_lshl_add_u64 v[224:225], v[136:137], 1, s[40:41]
	v_add_u32_e32 v136, 0x80, v136
	global_load_dwordx4 v[216:219], v[224:225], off
	v_lshl_add_u64 v[248:249], v[136:137], 1, s[40:41]
	global_load_dwordx4 v[220:223], v[248:249], off
	v_add_u32_e32 v136, 0x90, v167
	v_lshl_add_u32 v136, v136, 10, v168
	v_lshl_add_u64 v[224:225], v[136:137], 1, s[40:41]
	v_add_u32_e32 v136, 0x80, v136
	global_load_dwordx4 v[228:231], v[224:225], off
	v_lshl_add_u64 v[248:249], v[136:137], 1, s[40:41]
	global_load_dwordx4 v[244:247], v[248:249], off
	v_and_b32_e32 v166, 64, v165
	v_xor_b32_e32 v136, 16, v165
	v_add_u32_e32 v166, 64, v166
	v_cmp_lt_i32_e32 vcc, v136, v166
	s_lshl_b32 s11, s48, 2
	s_or_b32 s11, s11, s36
	v_cndmask_b32_e32 v136, v165, v136, vcc
	v_cmp_lt_i32_e32 vcc, v169, v166
	v_lshlrev_b32_e32 v166, 2, v136
	s_waitcnt vmcnt(10)
	v_cvt_f32_f16_e32 v182, v173
	v_cvt_f32_f16_sdwa v183, v173 dst_sel:DWORD dst_unused:UNUSED_PAD src0_sel:WORD_1
	v_cvt_f32_f16_e32 v184, v171
	v_cvt_f32_f16_sdwa v185, v171 dst_sel:DWORD dst_unused:UNUSED_PAD src0_sel:WORD_1
	v_cvt_f32_f16_e32 v186, v172
	v_cvt_f32_f16_sdwa v187, v172 dst_sel:DWORD dst_unused:UNUSED_PAD src0_sel:WORD_1
	v_cvt_f32_f16_e32 v172, v170
	v_cvt_f32_f16_sdwa v173, v170 dst_sel:DWORD dst_unused:UNUSED_PAD src0_sel:WORD_1
	v_cvt_f32_f16_e32 v170, v177
	v_cvt_f32_f16_sdwa v171, v177 dst_sel:DWORD dst_unused:UNUSED_PAD src0_sel:WORD_1
	v_cvt_f32_f16_e32 v188, v175
	v_cvt_f32_f16_sdwa v189, v175 dst_sel:DWORD dst_unused:UNUSED_PAD src0_sel:WORD_1
	v_cvt_f32_f16_e32 v190, v176
	v_cvt_f32_f16_sdwa v191, v176 dst_sel:DWORD dst_unused:UNUSED_PAD src0_sel:WORD_1
	v_cvt_f32_f16_e32 v176, v174
	v_cvt_f32_f16_sdwa v177, v174 dst_sel:DWORD dst_unused:UNUSED_PAD src0_sel:WORD_1
	v_pk_add_f32 v[124:125], v[124:125], v[172:173]
	v_pk_add_f32 v[172:173], v[120:121], v[186:187]
	v_pk_add_f32 v[126:127], v[126:127], v[184:185]
	v_pk_add_f32 v[122:123], v[122:123], v[182:183]
	v_cvt_pk_f16_f32 v120, v172, v173
	v_cvt_pk_f16_f32 v121, v122, v123
	v_pk_mul_f32 v[174:175], v[124:125], v[124:125]
	v_pk_mul_f32 v[182:183], v[126:127], v[126:127]
	v_pk_fma_f32 v[174:175], v[172:173], v[172:173], v[174:175]
	v_pk_fma_f32 v[182:183], v[122:123], v[122:123], v[182:183]
	v_pk_add_f32 v[176:177], v[116:117], v[176:177]
	v_pk_add_f32 v[116:117], v[112:113], v[190:191]
	v_pk_add_f32 v[184:185], v[118:119], v[188:189]
	v_pk_add_f32 v[112:113], v[114:115], v[170:171]
	v_pk_fma_f32 v[174:175], v[176:177], v[176:177], v[174:175]
	v_pk_fma_f32 v[182:183], v[184:185], v[184:185], v[182:183]
	v_pk_fma_f32 v[174:175], v[116:117], v[116:117], v[174:175]
	v_pk_fma_f32 v[182:183], v[112:113], v[112:113], v[182:183]
	v_pk_add_f32 v[174:175], v[174:175], v[182:183]
	v_add_f32_e32 v114, v174, v175
	v_mov_b32_e32 v115, v114
	s_nop 1
	v_permlane16_swap_b32_e32 v114, v115
	v_cndmask_b32_e32 v169, v165, v169, vcc
	v_cvt_pk_f16_f32 v119, v126, v127
	v_cvt_pk_f16_f32 v118, v124, v125
	global_store_dwordx4 v[178:179], v[118:121], off
	s_nop 1
	v_cvt_pk_f16_f32 v119, v112, v113
	s_waitcnt lgkmcnt(0)
	v_add_f32_e32 v113, v114, v115
	v_lshlrev_b32_e32 v112, 2, v169
	v_mov_b32_e32 v114, v113
	s_nop 1
	v_permlane32_swap_b32_e32 v113, v114
	v_cvt_pk_f16_f32 v118, v116, v117
	v_cvt_pk_f16_f32 v117, v184, v185
	v_cvt_pk_f16_f32 v116, v176, v177
	global_store_dwordx4 v[180:181], v[116:119], off
	s_and_saveexec_b64 s[48:49], s[4:5]
	s_cbranch_execz .LBB0_688
	v_lshl_add_u32 v136, v167, 4, s11
	s_waitcnt lgkmcnt(0)
	v_add_f32_e32 v113, v113, v114
	v_lshl_add_u64 v[114:115], v[136:137], 2, s[42:43]
	global_store_dword v[114:115], v113, off

; #define PG8_WAIT_V(n) asm volatile("s_waitcnt vmcnt(" #n ")" ::: "memory")
; template <class Epi, class Sched, bool ALIGN_EPI = false, bool SP2 = false, bool F16 = false, bool TOKPERM = false>
; __device__ __forceinline__ void gemm_phase(PG8_LAS unsigned char* lds, const Gemm g, const Sched& S, const Epi& E, int wv) {
;     ...
;     for (int i = 0; i < 2; ++i) { int R, C; stage_rc(tid * 16 + i * 8192, R, C); const int Rb = Epi::PERM ? ((R & ~31) + perm32(R & 31)) : R;
;         const int Ra = TOKPERM ? ((R & ~63) + 4 * (R & 15) + ((R >> 4) & 3)) : R;
;         voffA[i] = (unsigned)(Ra * K + C) * 2u; voffB[i] = (unsigned)(Rb * K + C) * 2u; }
;     const size_t kstep = (size_t)(BK * 2);
;     const size_t hstep = (size_t)HALF * K * 2;
;     const size_t tstep = 2 * hstep;
;     const unsigned ldsw = (unsigned)wid * 1024u;
;     const int aoff = lds_byte(wr * 64 + fr, fq * 8), boff = lds_byte(wc * 32 + fr, fq * 8);
;     ...
;     Unit cur, nxt; int ui = 0;
;     if (!S.next(0, cur)) return;
;     f32x4 acc[2][2][4][2];
; #pragma unroll
;     for (int a = 0; a < 2; ++a)
; #pragma unroll
;         for (int b = 0; b < 2; ++b)
; #pragma unroll
;             for (int m = 0; m < 4; ++m)
; #pragma unroll
;                 for (int n = 0; n < 2; ++n) acc[a][b][m][n] = (f32x4){0.f, 0.f, 0.f, 0.f};
;     bf16x8 At[4][2], B0[2][2], B1[2][2];
;     const char* cA = (const char*)g.A + (size_t)cur.pm * tstep; const char* cB = (const char*)g.Bt + (size_t)cur.pn * tstep;
;     S.a_ready(cur);
;     if constexpr (SP2) {
;         PG8_STAGE(PG8_SB(0, 0), cB, voffB); PG8_STAGE(PG8_SB(0, 1), cB + hstep, voffB); PG8_STAGE(PG8_SA(0, 0), cA, voffA); PG8_STAGE(PG8_SA(0, 1), cA + hstep, voffA);
;         if (wr == 1) PG8_BAR;
;         PG8_WAIT_V(2); PG8_BAR;
;         PG8_STAGE(PG8_SB(1, 0), cB + kstep, voffB); PG8_STAGE(PG8_SA(1, 0), cA + kstep, voffA); PG8_STAGE(PG8_SB(1, 1), cB + hstep + kstep, voffB);
;         PG8_WAIT_V(6); PG8_BAR;
;     } else {
;         PG8_STAGE(PG8_SB(0, 0), cB, voffB); PG8_STAGE(PG8_SA(0, 0), cA, voffA); PG8_STAGE(PG8_SB(0, 1), cB + hstep, voffB); PG8_STAGE(PG8_SA(0, 1), cA + hstep, voffA);
;         if (wr == 1) PG8_BAR;
;         PG8_WAIT_V(4); PG8_BAR;
;         PG8_STAGE(PG8_SB(1, 0), cB + kstep, voffB); PG8_STAGE(PG8_SA(1, 0), cA + kstep, voffA); PG8_STAGE(PG8_SB(1, 1), cB + hstep + kstep, voffB);
;         PG8_WAIT_V(6); PG8_BAR;
;     }
.LBB0_854:
	s_add_i32 s49, s3, 0x18000
	s_mov_b64 s[14:15], 0x80
	s_and_b32 s48, s6, 3
	v_lshl_add_u64 v[6:7], v[6:7], 0, s[14:15]
	s_mov_b32 m0, s49
	s_add_i32 s50, s3, 0x1a000
	s_lshl_b32 s6, s7, 13
	s_lshl_b32 s9, s48, 12
	s_waitcnt vmcnt(2)
	s_barrier
	global_load_lds_dwordx4 v[6:7], off
	v_lshl_add_u64 v[4:5], v[4:5], 0, s[14:15]
	s_mov_b32 m0, s50
	s_add_i32 s51, s3, 0x8000
	s_add_i32 s52, s3, 0xa000
	global_load_lds_dwordx4 v[4:5], off
	v_lshl_add_u64 v[2:3], v[2:3], 0, s[14:15]
	s_mov_b32 m0, s51
	s_add_u32 s10, s18, 0xb0080
	global_load_lds_dwordx4 v[2:3], off
	v_lshl_add_u64 v[0:1], v[0:1], 0, s[14:15]
	s_mov_b32 m0, s52
	s_addc_u32 s11, s19, 0
	s_add_i32 s53, s3, 0x1c000
	global_load_lds_dwordx4 v[0:1], off
	v_lshl_add_u64 v[0:1], s[10:11], 0, v[130:131]
	s_mov_b32 m0, s53
	s_add_i32 s54, s3, 0x1e000
	global_load_lds_dwordx4 v[0:1], off
	v_lshl_add_u64 v[0:1], s[10:11], 0, v[134:135]
	s_mov_b32 m0, s54
	s_mov_b64 s[10:11], 0xb0080
	global_load_lds_dwordx4 v[0:1], off
	v_bfe_u32 v0, v8, 4, 2
	v_and_b32_e32 v1, 15, v8
	v_lshlrev_b32_e32 v3, 4, v0
	v_lshl_or_b32 v146, s7, 6, v1
	v_lshl_or_b32 v1, v1, 6, v3
	v_lshlrev_b32_e32 v3, 2, v8
	v_and_b32_e32 v3, 32, v3
	v_lshlrev_b32_e32 v2, 3, v0
	v_bitop3_b32 v147, v1, s6, v3 bitop3:0xde
	v_bitop3_b32 v3, v1, s9, v3 bitop3:0xde
	v_cmp_eq_u32_e64 s[6:7], 0, v0
	v_lshrrev_b32_e32 v1, 1, v9
	v_mul_lo_u32 v0, v11, s8
	s_mov_b32 s9, 0xb000
	v_mad_u64_u32 v[0:1], s[12:13], v1, s9, v[0:1]
	v_or_b32_e32 v0, v0, v10
	v_add_lshl_u32 v136, v0, v12, 1
	v_lshrrev_b32_e32 v1, 1, v13
	v_mul_lo_u32 v0, v14, s8
	v_mad_u64_u32 v[0:1], s[8:9], v1, s9, v[0:1]
	s_waitcnt vmcnt(6)
	v_or_b32_e32 v0, v0, v15
	v_lshl_add_u64 v[138:139], v[136:137], 0, s[10:11]
	v_add_lshl_u32 v136, v0, v16, 1
	v_lshl_or_b32 v148, s48, 5, v2
	s_mov_b32 s55, 0
	s_ashr_i32 s56, s28, 31
	s_mov_b32 s57, s28
	s_ashr_i32 s58, s26, 31
	v_lshl_add_u64 v[140:141], v[136:137], 0, s[10:11]
	v_mov_b64_e32 v[142:143], 0x100
	v_mov_b64_e32 v[144:145], 0xff
	v_or_b32_e32 v149, 0x10000, v3
	v_add_u32_e32 v150, 0x10400, v3
	v_add_u32_e32 v151, 0x10800, v3
	v_add_u32_e32 v152, 0x10c00, v3
	v_or_b32_e32 v153, 0x14000, v3
	v_add_u32_e32 v154, 0x14400, v3
	v_add_u32_e32 v155, 0x14800, v3
	v_add_u32_e32 v156, 0x14c00, v3
	s_add_i32 s59, s3, 0xc000
	s_add_i32 s60, s3, 0xe000
	v_or_b32_e32 v157, 0x18000, v3
	v_add_u32_e32 v158, 0x18400, v3
	v_add_u32_e32 v159, 0x18800, v3
	v_add_u32_e32 v160, 0x18c00, v3
	v_or_b32_e32 v161, 0x1c000, v3
	v_add_u32_e32 v162, 0x1c400, v3
	v_add_u32_e32 v163, 0x1c800, v3
	v_add_u32_e32 v164, 0x1cc00, v3
	v_mbcnt_hi_u32_b32 v165, -1, v226
	s_barrier
	s_mov_b32 s99, 0
	s_branch .LBB0_856

; #define PG8_STAGE(bufoff, gbase, voff) do { _Pragma("unroll") for (int _i = 0; _i < 2; ++_i) \
;         __builtin_amdgcn_global_load_lds((const unsigned*)((const char*)(gbase) + (voff)[_i]), (PG8_LAS unsigned*)(lds + (bufoff) + ldsw + _i * 8192), 16, 0, 0); } while (0)
; #define PG8_LDA(dst, b, h) do { _Pragma("unroll") for (int m = 0; m < 4; ++m) _Pragma("unroll") for (int k = 0; k < 2; ++k) dst[m][k] = *(const PG8_LAS bf16x8*)(lds + PG8_SA(b, h) + aoff + m * 2048 + k * 1024); } while (0)
; #define PG8_LDB(dst, b, h) do { _Pragma("unroll") for (int n = 0; n < 2; ++n) _Pragma("unroll") for (int k = 0; k < 2; ++k) dst[n][k] = *(const PG8_LAS bf16x8*)(lds + PG8_SB(b, h) + boff + n * 2048 + k * 1024); } while (0)
; #define PG8_MMA(ai, bj, At, Bt) do { __builtin_amdgcn_s_setprio(1); _Pragma("unroll") for (int m = 0; m < 4; ++m) _Pragma("unroll") for (int n = 0; n < 2; ++n) _Pragma("unroll") for (int k = 0; k < 2; ++k) \
;         acc[ai][bj][m][n] = mma16<F16>(Bt[n][k], At[m][k], acc[ai][bj][m][n]); __builtin_amdgcn_s_setprio(0); } while (0)
; #define PG8_WAIT_V(n) asm volatile("s_waitcnt vmcnt(" #n ")" ::: "memory")
; #define PG8_WAIT_L(n) asm volatile("s_waitcnt lgkmcnt(" #n ")" ::: "memory")
; #define PG8_BAR __builtin_amdgcn_s_barrier()
; #define PG8_SCHED __builtin_amdgcn_sched_barrier(0)
; template <class Epi, class Sched, bool ALIGN_EPI = false, bool SP2 = false, bool F16 = false, bool TOKPERM = false>
; __device__ __forceinline__ void gemm_phase(PG8_LAS unsigned char* lds, const Gemm g, const Sched& S, const Epi& E, int wv) {
;     ...
;             PG8_LDB(B0, 0, 0); PG8_LDB(B1, 0, 1); PG8_SCHED; PG8_LDA(At, 0, 0); PG8_STAGE(PG8_SA(1, 1), a1 + hstep, voffA);
;             PG8_WAIT_V(8); PG8_WAIT_L(0); PG8_BAR; PG8_MMA(0, 0, At, B0); PG8_MMA(0, 1, At, B1); PG8_BAR; PG8_SCHED;
;             PG8_LDA(At, 0, 1); PG8_STAGE(PG8_SB(0, 0), b2, voffB); PG8_STAGE(PG8_SB(0, 1), b2 + hstep, voffB); PG8_STAGE(PG8_SA(0, 0), a2, voffA);
;             PG8_WAIT_V(8); PG8_WAIT_L(0); PG8_BAR; PG8_MMA(1, 0, At, B0); PG8_MMA(1, 1, At, B1); PG8_BAR; PG8_SCHED;
.LBB0_867:
	ds_read_b128 v[166:169], v149
	ds_read_b128 v[170:173], v150
	ds_read_b128 v[174:177], v151
	ds_read_b128 v[178:181], v152
	ds_read_b128 v[182:185], v153
	ds_read_b128 v[186:189], v154
	ds_read_b128 v[190:193], v155
	ds_read_b128 v[194:197], v156
	s_add_u32 s18, s16, 0x100
	s_addc_u32 s19, s17, 0
	s_cmp_eq_u32 s67, 40
	s_cselect_b32 s23, s11, s19
	s_cselect_b32 s22, s10, s18
	s_cselect_b32 s21, s13, s66
	s_cselect_b32 s20, s12, s65
	s_mov_b32 m0, s59
	v_lshl_add_u64 v[232:233], s[16:17], 0, v[138:139]
	ds_read_b128 v[198:201], v147
	ds_read_b128 v[202:205], v147 offset:1024
	ds_read_b128 v[206:209], v147 offset:2048
	ds_read_b128 v[210:213], v147 offset:3072
	ds_read_b128 v[214:217], v147 offset:4096
	ds_read_b128 v[218:221], v147 offset:5120
	ds_read_b128 v[222:225], v147 offset:6144
	ds_read_b128 v[228:231], v147 offset:7168
	global_load_lds_dwordx4 v[232:233], off
	v_lshl_add_u64 v[232:233], s[16:17], 0, v[140:141]
	s_mov_b32 m0, s60
	s_nop 0
	global_load_lds_dwordx4 v[232:233], off
	s_waitcnt vmcnt(24)
	s_cmp_eq_u32 s99, 1
	s_cbranch_scc1 .Lvmw_867_0
	s_waitcnt vmcnt(8)
.Lvmw_867_0:
	s_waitcnt lgkmcnt(0)
	s_barrier
	s_setprio 1
	s_waitcnt lgkmcnt(0)
	v_mfma_f32_16x16x32_bf16 v[124:127], v[166:169], v[198:201], v[124:127]
	v_mfma_f32_16x16x32_bf16 v[120:123], v[174:177], v[198:201], v[120:123]
	v_mfma_f32_16x16x32_bf16 v[108:111], v[166:169], v[206:209], v[108:111]
	v_mfma_f32_16x16x32_bf16 v[104:107], v[174:177], v[206:209], v[104:107]
	v_mfma_f32_16x16x32_bf16 v[92:95], v[166:169], v[214:217], v[92:95]
	v_mfma_f32_16x16x32_bf16 v[88:91], v[174:177], v[214:217], v[88:91]
	v_mfma_f32_16x16x32_bf16 v[76:79], v[166:169], v[222:225], v[76:79]
	v_mfma_f32_16x16x32_bf16 v[72:75], v[174:177], v[222:225], v[72:75]
	v_mfma_f32_16x16x32_bf16 v[124:127], v[170:173], v[202:205], v[124:127]
	v_mfma_f32_16x16x32_bf16 v[120:123], v[178:181], v[202:205], v[120:123]
	v_mfma_f32_16x16x32_bf16 v[108:111], v[170:173], v[210:213], v[108:111]
	v_mfma_f32_16x16x32_bf16 v[104:107], v[178:181], v[210:213], v[104:107]
	v_mfma_f32_16x16x32_bf16 v[92:95], v[170:173], v[218:221], v[92:95]
	v_mfma_f32_16x16x32_bf16 v[88:91], v[178:181], v[218:221], v[88:91]
	v_mfma_f32_16x16x32_bf16 v[76:79], v[170:173], v[228:231], v[76:79]
	v_mfma_f32_16x16x32_bf16 v[72:75], v[178:181], v[228:231], v[72:75]
	s_setprio 0
	s_setprio 1
	v_mfma_f32_16x16x32_bf16 v[116:119], v[182:185], v[198:201], v[116:119]
	v_mfma_f32_16x16x32_bf16 v[112:115], v[190:193], v[198:201], v[112:115]
	v_mfma_f32_16x16x32_bf16 v[100:103], v[182:185], v[206:209], v[100:103]
	v_mfma_f32_16x16x32_bf16 v[96:99], v[190:193], v[206:209], v[96:99]
	v_mfma_f32_16x16x32_bf16 v[84:87], v[182:185], v[214:217], v[84:87]
	v_mfma_f32_16x16x32_bf16 v[80:83], v[190:193], v[214:217], v[80:83]
	v_mfma_f32_16x16x32_bf16 v[68:71], v[182:185], v[222:225], v[68:71]
	v_mfma_f32_16x16x32_bf16 v[64:67], v[190:193], v[222:225], v[64:67]
	v_mfma_f32_16x16x32_bf16 v[116:119], v[186:189], v[202:205], v[116:119]
	v_mfma_f32_16x16x32_bf16 v[112:115], v[194:197], v[202:205], v[112:115]
	v_mfma_f32_16x16x32_bf16 v[100:103], v[186:189], v[210:213], v[100:103]
	v_mfma_f32_16x16x32_bf16 v[96:99], v[194:197], v[210:213], v[96:99]
	v_mfma_f32_16x16x32_bf16 v[84:87], v[186:189], v[218:221], v[84:87]
	v_mfma_f32_16x16x32_bf16 v[80:83], v[194:197], v[218:221], v[80:83]
	v_mfma_f32_16x16x32_bf16 v[68:71], v[186:189], v[228:231], v[68:71]
	v_mfma_f32_16x16x32_bf16 v[64:67], v[194:197], v[228:231], v[64:67]
	s_setprio 0
	s_barrier
	s_mov_b32 m0, s4
	v_lshl_add_u64 v[232:233], s[20:21], 0, v[130:131]
	s_add_u32 s16, s20, 0xb0000
	ds_read_b128 v[198:201], v147 offset:16384
	ds_read_b128 v[202:205], v147 offset:17408
	ds_read_b128 v[206:209], v147 offset:18432
	ds_read_b128 v[210:213], v147 offset:19456
	ds_read_b128 v[214:217], v147 offset:20480
	ds_read_b128 v[218:221], v147 offset:21504
	ds_read_b128 v[222:225], v147 offset:22528
	ds_read_b128 v[228:231], v147 offset:23552
	global_load_lds_dwordx4 v[232:233], off
	v_lshl_add_u64 v[234:235], s[20:21], 0, v[134:135]
	s_mov_b32 m0, s5
	s_addc_u32 s17, s21, 0
	global_load_lds_dwordx4 v[234:235], off
	v_lshl_add_u64 v[236:237], s[16:17], 0, v[130:131]
	s_mov_b32 m0, s33
	v_lshl_add_u64 v[238:239], s[22:23], 0, v[132:133]
	global_load_lds_dwordx4 v[236:237], off
	v_lshl_add_u64 v[236:237], s[16:17], 0, v[134:135]
	s_mov_b32 m0, s36
	s_nop 0
	global_load_lds_dwordx4 v[236:237], off
	v_lshl_add_u64 v[236:237], s[22:23], 0, v[128:129]
	s_mov_b32 m0, s3
	s_nop 0
	global_load_lds_dwordx4 v[236:237], off
	s_mov_b32 m0, s37
	s_nop 0
	global_load_lds_dwordx4 v[238:239], off
	s_waitcnt vmcnt(24)
	s_cmp_eq_u32 s99, 1
	s_cbranch_scc1 .Lvmw_867_1
	s_waitcnt vmcnt(8)
; #define PG8_STAGE(bufoff, gbase, voff) do { _Pragma("unroll") for (int _i = 0; _i < 2; ++_i) \
;         __builtin_amdgcn_global_load_lds((const unsigned*)((const char*)(gbase) + (voff)[_i]), (PG8_LAS unsigned*)(lds + (bufoff) + ldsw + _i * 8192), 16, 0, 0); } while (0)
; #define PG8_LDA(dst, b, h) do { _Pragma("unroll") for (int m = 0; m < 4; ++m) _Pragma("unroll") for (int k = 0; k < 2; ++k) dst[m][k] = *(const PG8_LAS bf16x8*)(lds + PG8_SA(b, h) + aoff + m * 2048 + k * 1024); } while (0)
; #define PG8_LDB(dst, b, h) do { _Pragma("unroll") for (int n = 0; n < 2; ++n) _Pragma("unroll") for (int k = 0; k < 2; ++k) dst[n][k] = *(const PG8_LAS bf16x8*)(lds + PG8_SB(b, h) + boff + n * 2048 + k * 1024); } while (0)
; #define PG8_MMA(ai, bj, At, Bt) do { __builtin_amdgcn_s_setprio(1); _Pragma("unroll") for (int m = 0; m < 4; ++m) _Pragma("unroll") for (int n = 0; n < 2; ++n) _Pragma("unroll") for (int k = 0; k < 2; ++k) \
;         acc[ai][bj][m][n] = mma16<F16>(Bt[n][k], At[m][k], acc[ai][bj][m][n]); __builtin_amdgcn_s_setprio(0); } while (0)
; #define PG8_WAIT_V(n) asm volatile("s_waitcnt vmcnt(" #n ")" ::: "memory")
; #define PG8_WAIT_L(n) asm volatile("s_waitcnt lgkmcnt(" #n ")" ::: "memory")
; #define PG8_BAR __builtin_amdgcn_s_barrier()
; #define PG8_SCHED __builtin_amdgcn_sched_barrier(0)
; template <class Epi, class Sched, bool ALIGN_EPI = false, bool SP2 = false, bool F16 = false, bool TOKPERM = false>
; __device__ __forceinline__ void gemm_phase(PG8_LAS unsigned char* lds, const Gemm g, const Sched& S, const Epi& E, int wv) {
;     ...
;             PG8_WAIT_V(8); PG8_WAIT_L(0); PG8_BAR; PG8_MMA(1, 0, At, B0); PG8_MMA(1, 1, At, B1); PG8_BAR; PG8_SCHED;
;             PG8_LDB(B0, 1, 0); PG8_LDB(B1, 1, 1); PG8_SCHED; PG8_LDA(At, 1, 0); PG8_STAGE(PG8_SA(0, 1), a2 + hstep, voffA);
;             PG8_WAIT_V(8); PG8_WAIT_L(0); PG8_BAR; PG8_MMA(0, 0, At, B0); PG8_MMA(0, 1, At, B1); PG8_BAR; PG8_SCHED;
.Lvmw_867_1:
	s_mov_b32 s99, 0
	s_waitcnt lgkmcnt(0)
	s_barrier
	s_setprio 1
	s_waitcnt lgkmcnt(0)
	v_mfma_f32_16x16x32_bf16 v[60:63], v[166:169], v[198:201], v[60:63]
	v_mfma_f32_16x16x32_bf16 v[56:59], v[174:177], v[198:201], v[56:59]
	v_mfma_f32_16x16x32_bf16 v[44:47], v[166:169], v[206:209], v[44:47]
	v_mfma_f32_16x16x32_bf16 v[40:43], v[174:177], v[206:209], v[40:43]
	v_mfma_f32_16x16x32_bf16 v[28:31], v[166:169], v[214:217], v[28:31]
	v_mfma_f32_16x16x32_bf16 v[24:27], v[174:177], v[214:217], v[24:27]
	v_mfma_f32_16x16x32_bf16 v[12:15], v[166:169], v[222:225], v[12:15]
	v_mfma_f32_16x16x32_bf16 v[8:11], v[174:177], v[222:225], v[8:11]
	v_mfma_f32_16x16x32_bf16 v[60:63], v[170:173], v[202:205], v[60:63]
	v_mfma_f32_16x16x32_bf16 v[56:59], v[178:181], v[202:205], v[56:59]
	v_mfma_f32_16x16x32_bf16 v[44:47], v[170:173], v[210:213], v[44:47]
	v_mfma_f32_16x16x32_bf16 v[40:43], v[178:181], v[210:213], v[40:43]
	v_mfma_f32_16x16x32_bf16 v[28:31], v[170:173], v[218:221], v[28:31]
	v_mfma_f32_16x16x32_bf16 v[24:27], v[178:181], v[218:221], v[24:27]
	v_mfma_f32_16x16x32_bf16 v[12:15], v[170:173], v[228:231], v[12:15]
	v_mfma_f32_16x16x32_bf16 v[8:11], v[178:181], v[228:231], v[8:11]
	s_setprio 0
	s_setprio 1
	v_mfma_f32_16x16x32_bf16 v[52:55], v[182:185], v[198:201], v[52:55]
	v_mfma_f32_16x16x32_bf16 v[48:51], v[190:193], v[198:201], v[48:51]
	v_mfma_f32_16x16x32_bf16 v[36:39], v[182:185], v[206:209], v[36:39]
	v_mfma_f32_16x16x32_bf16 v[32:35], v[190:193], v[206:209], v[32:35]
	v_mfma_f32_16x16x32_bf16 v[20:23], v[182:185], v[214:217], v[20:23]
	v_mfma_f32_16x16x32_bf16 v[16:19], v[190:193], v[214:217], v[16:19]
	v_mfma_f32_16x16x32_bf16 v[4:7], v[182:185], v[222:225], v[4:7]
	v_mfma_f32_16x16x32_bf16 v[0:3], v[190:193], v[222:225], v[0:3]
	v_mfma_f32_16x16x32_bf16 v[52:55], v[186:189], v[202:205], v[52:55]
	v_mfma_f32_16x16x32_bf16 v[48:51], v[194:197], v[202:205], v[48:51]
	v_mfma_f32_16x16x32_bf16 v[36:39], v[186:189], v[210:213], v[36:39]
	v_mfma_f32_16x16x32_bf16 v[32:35], v[194:197], v[210:213], v[32:35]
	v_mfma_f32_16x16x32_bf16 v[20:23], v[186:189], v[218:221], v[20:23]
	v_mfma_f32_16x16x32_bf16 v[16:19], v[194:197], v[218:221], v[16:19]
	v_mfma_f32_16x16x32_bf16 v[4:7], v[186:189], v[228:231], v[4:7]
	v_mfma_f32_16x16x32_bf16 v[0:3], v[194:197], v[228:231], v[0:3]
	s_setprio 0
	s_barrier
	ds_read_b128 v[166:169], v157
	ds_read_b128 v[170:173], v158
	ds_read_b128 v[174:177], v159
	ds_read_b128 v[178:181], v160
	ds_read_b128 v[182:185], v161
	ds_read_b128 v[186:189], v162
	ds_read_b128 v[190:193], v163
	ds_read_b128 v[194:197], v164
	s_add_u32 s16, s22, 0xb0000
	s_addc_u32 s17, s23, 0
	s_mov_b32 m0, s44
	v_lshl_add_u64 v[240:241], s[16:17], 0, v[128:129]
	ds_read_b128 v[198:201], v147 offset:32768
	ds_read_b128 v[202:205], v147 offset:33792
	ds_read_b128 v[206:209], v147 offset:34816
	ds_read_b128 v[210:213], v147 offset:35840
	ds_read_b128 v[214:217], v147 offset:36864
	ds_read_b128 v[218:221], v147 offset:37888
	ds_read_b128 v[222:225], v147 offset:38912
	ds_read_b128 v[228:231], v147 offset:39936
	global_load_lds_dwordx4 v[240:241], off
	v_lshl_add_u64 v[240:241], s[16:17], 0, v[132:133]
	s_mov_b32 m0, s45
	s_nop 0
	global_load_lds_dwordx4 v[240:241], off
	s_waitcnt vmcnt(8)
	s_waitcnt lgkmcnt(0)
	s_barrier
	s_setprio 1
	s_waitcnt lgkmcnt(0)
	v_mfma_f32_16x16x32_bf16 v[124:127], v[166:169], v[198:201], v[124:127]
	v_mfma_f32_16x16x32_bf16 v[120:123], v[174:177], v[198:201], v[120:123]
	v_mfma_f32_16x16x32_bf16 v[108:111], v[166:169], v[206:209], v[108:111]
	v_mfma_f32_16x16x32_bf16 v[104:107], v[174:177], v[206:209], v[104:107]
	v_mfma_f32_16x16x32_bf16 v[92:95], v[166:169], v[214:217], v[92:95]
	v_mfma_f32_16x16x32_bf16 v[88:91], v[174:177], v[214:217], v[88:91]
	v_mfma_f32_16x16x32_bf16 v[76:79], v[166:169], v[222:225], v[76:79]
	v_mfma_f32_16x16x32_bf16 v[72:75], v[174:177], v[222:225], v[72:75]
	v_mfma_f32_16x16x32_bf16 v[124:127], v[170:173], v[202:205], v[124:127]
	v_mfma_f32_16x16x32_bf16 v[120:123], v[178:181], v[202:205], v[120:123]
	v_mfma_f32_16x16x32_bf16 v[108:111], v[170:173], v[210:213], v[108:111]
	v_mfma_f32_16x16x32_bf16 v[104:107], v[178:181], v[210:213], v[104:107]
	v_mfma_f32_16x16x32_bf16 v[92:95], v[170:173], v[218:221], v[92:95]
	v_mfma_f32_16x16x32_bf16 v[88:91], v[178:181], v[218:221], v[88:91]
	v_mfma_f32_16x16x32_bf16 v[76:79], v[170:173], v[228:231], v[76:79]
	v_mfma_f32_16x16x32_bf16 v[72:75], v[178:181], v[228:231], v[72:75]
	s_setprio 0
	s_setprio 1
	v_mfma_f32_16x16x32_bf16 v[116:119], v[182:185], v[198:201], v[116:119]
	v_mfma_f32_16x16x32_bf16 v[112:115], v[190:193], v[198:201], v[112:115]
	v_mfma_f32_16x16x32_bf16 v[100:103], v[182:185], v[206:209], v[100:103]
	v_mfma_f32_16x16x32_bf16 v[96:99], v[190:193], v[206:209], v[96:99]
	v_mfma_f32_16x16x32_bf16 v[84:87], v[182:185], v[214:217], v[84:87]
	v_mfma_f32_16x16x32_bf16 v[80:83], v[190:193], v[214:217], v[80:83]
	v_mfma_f32_16x16x32_bf16 v[68:71], v[182:185], v[222:225], v[68:71]
	v_mfma_f32_16x16x32_bf16 v[64:67], v[190:193], v[222:225], v[64:67]
	v_mfma_f32_16x16x32_bf16 v[116:119], v[186:189], v[202:205], v[116:119]
	v_mfma_f32_16x16x32_bf16 v[112:115], v[194:197], v[202:205], v[112:115]
	v_mfma_f32_16x16x32_bf16 v[100:103], v[186:189], v[210:213], v[100:103]
	v_mfma_f32_16x16x32_bf16 v[96:99], v[194:197], v[210:213], v[96:99]
	v_mfma_f32_16x16x32_bf16 v[84:87], v[186:189], v[218:221], v[84:87]
	v_mfma_f32_16x16x32_bf16 v[80:83], v[194:197], v[218:221], v[80:83]
	v_mfma_f32_16x16x32_bf16 v[68:71], v[186:189], v[228:231], v[68:71]
	v_mfma_f32_16x16x32_bf16 v[64:67], v[194:197], v[228:231], v[64:67]
	s_setprio 0
	s_barrier
; #define PG8_STAGE(bufoff, gbase, voff) do { _Pragma("unroll") for (int _i = 0; _i < 2; ++_i) \
;         __builtin_amdgcn_global_load_lds((const unsigned*)((const char*)(gbase) + (voff)[_i]), (PG8_LAS unsigned*)(lds + (bufoff) + ldsw + _i * 8192), 16, 0, 0); } while (0)
; #define PG8_LDA(dst, b, h) do { _Pragma("unroll") for (int m = 0; m < 4; ++m) _Pragma("unroll") for (int k = 0; k < 2; ++k) dst[m][k] = *(const PG8_LAS bf16x8*)(lds + PG8_SA(b, h) + aoff + m * 2048 + k * 1024); } while (0)
; #define PG8_MMA(ai, bj, At, Bt) do { __builtin_amdgcn_s_setprio(1); _Pragma("unroll") for (int m = 0; m < 4; ++m) _Pragma("unroll") for (int n = 0; n < 2; ++n) _Pragma("unroll") for (int k = 0; k < 2; ++k) \
;         acc[ai][bj][m][n] = mma16<F16>(Bt[n][k], At[m][k], acc[ai][bj][m][n]); __builtin_amdgcn_s_setprio(0); } while (0)
; #define PG8_WAIT_V(n) asm volatile("s_waitcnt vmcnt(" #n ")" ::: "memory")
; #define PG8_WAIT_L(n) asm volatile("s_waitcnt lgkmcnt(" #n ")" ::: "memory")
; #define PG8_BAR __builtin_amdgcn_s_barrier()
; #define PG8_SCHED __builtin_amdgcn_sched_barrier(0)
; template <class Epi, class Sched, bool ALIGN_EPI = false, bool SP2 = false, bool F16 = false, bool TOKPERM = false>
; __device__ __forceinline__ void gemm_phase(PG8_LAS unsigned char* lds, const Gemm g, const Sched& S, const Epi& E, int wv) {
;     ...
;             PG8_LDA(At, 1, 1); PG8_STAGE(PG8_SB(1, 0), b3, voffB); PG8_STAGE(PG8_SB(1, 1), b3 + hstep, voffB); PG8_STAGE(PG8_SA(1, 0), a3, voffA);
;             PG8_WAIT_V(8); PG8_WAIT_L(0); PG8_BAR; PG8_MMA(1, 0, At, B0); PG8_MMA(1, 1, At, B1); PG8_BAR; PG8_SCHED;
	s_mov_b32 m0, s49
	v_lshl_add_u64 v[232:233], v[232:233], 0, s[14:15]
	s_add_u32 s16, s20, 0xb0080
	ds_read_b128 v[198:201], v147 offset:49152
	ds_read_b128 v[202:205], v147 offset:50176
	ds_read_b128 v[206:209], v147 offset:51200
	ds_read_b128 v[210:213], v147 offset:52224
	ds_read_b128 v[214:217], v147 offset:53248
	ds_read_b128 v[218:221], v147 offset:54272
	ds_read_b128 v[222:225], v147 offset:55296
	ds_read_b128 v[228:231], v147 offset:56320
	global_load_lds_dwordx4 v[232:233], off
	v_lshl_add_u64 v[232:233], v[234:235], 0, s[14:15]
	s_mov_b32 m0, s50
	s_addc_u32 s17, s21, 0
	global_load_lds_dwordx4 v[232:233], off
	v_lshl_add_u64 v[232:233], s[16:17], 0, v[130:131]
	s_mov_b32 m0, s53
	s_nop 0
	global_load_lds_dwordx4 v[232:233], off
	v_lshl_add_u64 v[232:233], s[16:17], 0, v[134:135]
	s_mov_b32 m0, s54
	s_nop 0
	global_load_lds_dwordx4 v[232:233], off
	v_lshl_add_u64 v[232:233], v[236:237], 0, s[14:15]
	s_mov_b32 m0, s51
	s_nop 0
	global_load_lds_dwordx4 v[232:233], off
	v_lshl_add_u64 v[232:233], v[238:239], 0, s[14:15]
	s_mov_b32 m0, s52
	s_nop 0
	global_load_lds_dwordx4 v[232:233], off
	s_waitcnt vmcnt(8)
	s_waitcnt lgkmcnt(0)
	s_barrier
	s_setprio 1
	s_waitcnt lgkmcnt(0)
	v_mfma_f32_16x16x32_bf16 v[60:63], v[166:169], v[198:201], v[60:63]
	v_mfma_f32_16x16x32_bf16 v[56:59], v[174:177], v[198:201], v[56:59]
	v_mfma_f32_16x16x32_bf16 v[44:47], v[166:169], v[206:209], v[44:47]
	v_mfma_f32_16x16x32_bf16 v[40:43], v[174:177], v[206:209], v[40:43]
	v_mfma_f32_16x16x32_bf16 v[28:31], v[166:169], v[214:217], v[28:31]
	v_mfma_f32_16x16x32_bf16 v[24:27], v[174:177], v[214:217], v[24:27]
	v_mfma_f32_16x16x32_bf16 v[12:15], v[166:169], v[222:225], v[12:15]
	v_mfma_f32_16x16x32_bf16 v[8:11], v[174:177], v[222:225], v[8:11]
	v_mfma_f32_16x16x32_bf16 v[60:63], v[170:173], v[202:205], v[60:63]
	v_mfma_f32_16x16x32_bf16 v[56:59], v[178:181], v[202:205], v[56:59]
	v_mfma_f32_16x16x32_bf16 v[44:47], v[170:173], v[210:213], v[44:47]
	v_mfma_f32_16x16x32_bf16 v[40:43], v[178:181], v[210:213], v[40:43]
	v_mfma_f32_16x16x32_bf16 v[28:31], v[170:173], v[218:221], v[28:31]
	v_mfma_f32_16x16x32_bf16 v[24:27], v[178:181], v[218:221], v[24:27]
	v_mfma_f32_16x16x32_bf16 v[12:15], v[170:173], v[228:231], v[12:15]
	v_mfma_f32_16x16x32_bf16 v[8:11], v[178:181], v[228:231], v[8:11]
	s_setprio 0
	s_setprio 1
	v_mfma_f32_16x16x32_bf16 v[52:55], v[182:185], v[198:201], v[52:55]
	v_mfma_f32_16x16x32_bf16 v[48:51], v[190:193], v[198:201], v[48:51]
	v_mfma_f32_16x16x32_bf16 v[36:39], v[182:185], v[206:209], v[36:39]
	v_mfma_f32_16x16x32_bf16 v[32:35], v[190:193], v[206:209], v[32:35]
	v_mfma_f32_16x16x32_bf16 v[20:23], v[182:185], v[214:217], v[20:23]
	v_mfma_f32_16x16x32_bf16 v[16:19], v[190:193], v[214:217], v[16:19]
	v_mfma_f32_16x16x32_bf16 v[4:7], v[182:185], v[222:225], v[4:7]
	v_mfma_f32_16x16x32_bf16 v[0:3], v[190:193], v[222:225], v[0:3]
	v_mfma_f32_16x16x32_bf16 v[52:55], v[186:189], v[202:205], v[52:55]
	v_mfma_f32_16x16x32_bf16 v[48:51], v[194:197], v[202:205], v[48:51]
	v_mfma_f32_16x16x32_bf16 v[36:39], v[186:189], v[210:213], v[36:39]
	v_mfma_f32_16x16x32_bf16 v[32:35], v[194:197], v[210:213], v[32:35]
	v_mfma_f32_16x16x32_bf16 v[20:23], v[186:189], v[218:221], v[20:23]
	v_mfma_f32_16x16x32_bf16 v[16:19], v[194:197], v[218:221], v[16:19]
	v_mfma_f32_16x16x32_bf16 v[4:7], v[186:189], v[228:231], v[4:7]
	v_mfma_f32_16x16x32_bf16 v[0:3], v[194:197], v[228:231], v[0:3]
	s_setprio 0
	s_barrier
	s_add_i32 s67, s67, 2
	s_add_u32 s65, s65, 0x100
	s_addc_u32 s66, s66, 0
	s_cmp_gt_u32 s67, 41
	s_mov_b64 s[16:17], s[18:19]
	s_cbranch_scc0 .LBB0_867
;   __device__ __forceinline__ void operator()(const pg8::f32x4 (&acc)[2][2][4][2], const pg8::Unit& u, int wr, int wc, int fr, int fq) const {
;     int z; asm volatile("v_mov_b32 %0, 0" : "=v"(z));
;     const int row0 = u.pm * 256 + wr * 64 + fr + z, colb = u.pn * 256 + wc * 32 + 8 * fq + z;
; #pragma unroll
;     for (int ai = 0; ai < 2; ++ai)
; #pragma unroll
;       for (int m = 0; m < 4; ++m) {
;         const int tok = row0 + ai * 128 + m * 16; float ss = 0.f;
; #pragma unroll
;         for (int bj = 0; bj < 2; ++bj) {
;           const unsigned off = (unsigned)tok * DM + colb + 128 * bj;
;           f8_t n = __builtin_convertvector(*(const h8_t*)(x16 + off), f8_t);
; #pragma unroll
;           for (int c = 0; c < 4; ++c) { n[c] += sc * acc[ai][bj][m][0][c]; n[4 + c] += sc * acc[ai][bj][m][1][c]; }
;           if (aux) {
;             *(h8_t*)(x16 + off) = __builtin_convertvector(n, h8_t);
;             ss += ((n[0] * n[0] + n[1] * n[1]) + (n[2] * n[2] + n[3] * n[3])) + ((n[4] * n[4] + n[5] * n[5]) + (n[6] * n[6] + n[7] * n[7]));
;           } else {
;             *(f32x4*)(xout + off) = (f32x4){n[0], n[1], n[2], n[3]}; *(f32x4*)(xout + off + 4) = (f32x4){n[4], n[5], n[6], n[7]};
;           }
;         }
;         if (aux) { ss += __shfl_xor(ss, 16); ss += __shfl_xor(ss, 32); if (fq == 0) ssq[(unsigned)tok * 16 + u.pn * 4 + wc] = ss; }
;         if (m & 1) asm volatile("" ::: "memory");
;       }
;   }
	s_mov_b32 s99, 1
	s_lshl_b32 s16, s64, 8
	v_lshl_or_b32 v166, s63, 8, v148
	v_mov_b32 v136, 0
	v_xor_b32_e32 v169, 32, v165
	v_add3_u32 v167, s16, v146, v136
	v_add_u32_e32 v168, v166, v136
	v_lshl_add_u32 v136, v167, 10, v168
	v_lshl_add_u64 v[178:179], v[136:137], 1, s[40:41]
	v_add_u32_e32 v136, 0x80, v136
	global_load_dwordx4 v[170:173], v[178:179], off
	v_lshl_add_u64 v[180:181], v[136:137], 1, s[40:41]
	global_load_dwordx4 v[174:177], v[180:181], off
	v_add_u32_e32 v136, 16, v167
	v_lshl_add_u32 v136, v136, 10, v168
	v_lshl_add_u64 v[224:225], v[136:137], 1, s[40:41]
	v_add_u32_e32 v136, 0x80, v136
	global_load_dwordx4 v[192:195], v[224:225], off
	v_lshl_add_u64 v[248:249], v[136:137], 1, s[40:41]
	global_load_dwordx4 v[196:199], v[248:249], off
	v_add_u32_e32 v136, 32, v167
	v_lshl_add_u32 v136, v136, 10, v168
	v_lshl_add_u64 v[224:225], v[136:137], 1, s[40:41]
	v_add_u32_e32 v136, 0x80, v136
	global_load_dwordx4 v[200:203], v[224:225], off
	v_lshl_add_u64 v[248:249], v[136:137], 1, s[40:41]
	global_load_dwordx4 v[204:207], v[248:249], off
	v_add_u32_e32 v136, 48, v167
	v_lshl_add_u32 v136, v136, 10, v168
	v_lshl_add_u64 v[224:225], v[136:137], 1, s[40:41]
	v_add_u32_e32 v136, 0x80, v136
	global_load_dwordx4 v[208:211], v[224:225], off
	v_lshl_add_u64 v[248:249], v[136:137], 1, s[40:41]
	global_load_dwordx4 v[212:215], v[248:249], off
	v_add_u32_e32 v136, 0x80, v167
	v_lshl_add_u32 v136, v136, 10, v168
	v_lshl_add_u64 v[224:225], v[136:137], 1, s[40:41]
	v_add_u32_e32 v136, 0x80, v136
	global_load_dwordx4 v[216:219], v[224:225], off
	v_lshl_add_u64 v[248:249], v[136:137], 1, s[40:41]
	global_load_dwordx4 v[220:223], v[248:249], off
	v_add_u32_e32 v136, 0x90, v167
	v_lshl_add_u32 v136, v136, 10, v168
	v_lshl_add_u64 v[224:225], v[136:137], 1, s[40:41]
	v_add_u32_e32 v136, 0x80, v136
	global_load_dwordx4 v[228:231], v[224:225], off
	v_lshl_add_u64 v[248:249], v[136:137], 1, s[40:41]
	global_load_dwordx4 v[244:247], v[248:249], off
	v_and_b32_e32 v166, 64, v165
	v_xor_b32_e32 v136, 16, v165
	v_add_u32_e32 v166, 64, v166
	v_cmp_lt_i32_e32 vcc, v136, v166
	s_lshl_b32 s16, s63, 2
	s_or_b32 s18, s16, s48
	v_cndmask_b32_e32 v136, v165, v136, vcc
	v_cmp_lt_i32_e32 vcc, v169, v166
	v_lshlrev_b32_e32 v166, 2, v136
	s_waitcnt vmcnt(10)
	v_cvt_f32_f16_e32 v182, v173
	v_cvt_f32_f16_sdwa v183, v173 dst_sel:DWORD dst_unused:UNUSED_PAD src0_sel:WORD_1
	v_cvt_f32_f16_e32 v184, v171
	v_cvt_f32_f16_sdwa v185, v171 dst_sel:DWORD dst_unused:UNUSED_PAD src0_sel:WORD_1
	v_cvt_f32_f16_e32 v186, v172
	v_cvt_f32_f16_sdwa v187, v172 dst_sel:DWORD dst_unused:UNUSED_PAD src0_sel:WORD_1
	v_cvt_f32_f16_e32 v172, v170
	v_cvt_f32_f16_sdwa v173, v170 dst_sel:DWORD dst_unused:UNUSED_PAD src0_sel:WORD_1
	v_cvt_f32_f16_e32 v170, v177
	v_cvt_f32_f16_sdwa v171, v177 dst_sel:DWORD dst_unused:UNUSED_PAD src0_sel:WORD_1
	v_cvt_f32_f16_e32 v188, v175
	v_cvt_f32_f16_sdwa v189, v175 dst_sel:DWORD dst_unused:UNUSED_PAD src0_sel:WORD_1
	v_cvt_f32_f16_e32 v190, v176
	v_cvt_f32_f16_sdwa v191, v176 dst_sel:DWORD dst_unused:UNUSED_PAD src0_sel:WORD_1
	v_cvt_f32_f16_e32 v176, v174
	v_cvt_f32_f16_sdwa v177, v174 dst_sel:DWORD dst_unused:UNUSED_PAD src0_sel:WORD_1
	v_pk_fma_f32 v[124:125], v[124:125], 0.5, v[172:173] op_sel_hi:[1,0,1]
	v_pk_fma_f32 v[172:173], v[120:121], 0.5, v[186:187] op_sel_hi:[1,0,1]
	v_pk_fma_f32 v[126:127], v[126:127], 0.5, v[184:185] op_sel_hi:[1,0,1]
	v_pk_fma_f32 v[122:123], v[122:123], 0.5, v[182:183] op_sel_hi:[1,0,1]
	v_cvt_pk_f16_f32 v120, v172, v173
	v_cvt_pk_f16_f32 v121, v122, v123
	v_pk_mul_f32 v[174:175], v[124:125], v[124:125]
	v_pk_mul_f32 v[182:183], v[126:127], v[126:127]
	v_pk_fma_f32 v[174:175], v[172:173], v[172:173], v[174:175]
	v_pk_fma_f32 v[182:183], v[122:123], v[122:123], v[182:183]
	v_pk_fma_f32 v[176:177], v[116:117], 0.5, v[176:177] op_sel_hi:[1,0,1]
	v_pk_fma_f32 v[116:117], v[112:113], 0.5, v[190:191] op_sel_hi:[1,0,1]
	v_pk_fma_f32 v[184:185], v[118:119], 0.5, v[188:189] op_sel_hi:[1,0,1]
	v_pk_fma_f32 v[112:113], v[114:115], 0.5, v[170:171] op_sel_hi:[1,0,1]
	v_pk_fma_f32 v[174:175], v[176:177], v[176:177], v[174:175]
	v_pk_fma_f32 v[182:183], v[184:185], v[184:185], v[182:183]
	v_pk_fma_f32 v[174:175], v[116:117], v[116:117], v[174:175]
	v_pk_fma_f32 v[182:183], v[112:113], v[112:113], v[182:183]
	v_pk_add_f32 v[174:175], v[174:175], v[182:183]
	v_add_f32_e32 v114, v174, v175
	v_mov_b32_e32 v115, v114
	s_nop 1
	v_permlane16_swap_b32_e32 v114, v115
	v_cndmask_b32_e32 v169, v165, v169, vcc
	v_cvt_pk_f16_f32 v119, v126, v127
	v_cvt_pk_f16_f32 v118, v124, v125
	global_store_dwordx4 v[178:179], v[118:121], off
	s_nop 1
	v_cvt_pk_f16_f32 v119, v112, v113
	s_waitcnt lgkmcnt(0)
	v_add_f32_e32 v113, v114, v115
	v_lshlrev_b32_e32 v112, 2, v169
	v_mov_b32_e32 v114, v113
	s_nop 1
	v_permlane32_swap_b32_e32 v113, v114
	v_cvt_pk_f16_f32 v118, v116, v117
	v_cvt_pk_f16_f32 v117, v184, v185
	v_cvt_pk_f16_f32 v116, v176, v177
	global_store_dwordx4 v[180:181], v[116:119], off
	s_and_saveexec_b64 s[16:17], s[6:7]
	s_cbranch_execz .LBB0_870
	v_lshl_add_u32 v136, v167, 4, s18
	s_waitcnt lgkmcnt(0)
	v_add_f32_e32 v113, v113, v114
	v_lshl_add_u64 v[114:115], v[136:137], 2, s[42:43]
	global_store_dword v[114:115], v113, off

; #define PG8_WAIT_V(n) asm volatile("s_waitcnt vmcnt(" #n ")" ::: "memory")
; template <class Epi, class Sched, bool ALIGN_EPI = false, bool SP2 = false, bool F16 = false, bool TOKPERM = false>
; __device__ __forceinline__ void gemm_phase(PG8_LAS unsigned char* lds, const Gemm g, const Sched& S, const Epi& E, int wv) {
;     ...
;     for (int i = 0; i < 2; ++i) { int R, C; stage_rc(tid * 16 + i * 8192, R, C); const int Rb = Epi::PERM ? ((R & ~31) + perm32(R & 31)) : R;
;         const int Ra = TOKPERM ? ((R & ~63) + 4 * (R & 15) + ((R >> 4) & 3)) : R;
;         voffA[i] = (unsigned)(Ra * K + C) * 2u; voffB[i] = (unsigned)(Rb * K + C) * 2u; }
;     const size_t kstep = (size_t)(BK * 2);
;     const size_t hstep = (size_t)HALF * K * 2;
;     const size_t tstep = 2 * hstep;
;     const unsigned ldsw = (unsigned)wid * 1024u;
;     const int aoff = lds_byte(wr * 64 + fr, fq * 8), boff = lds_byte(wc * 32 + fr, fq * 8);
;     ...
;     Unit cur, nxt; int ui = 0;
;     if (!S.next(0, cur)) return;
;     f32x4 acc[2][2][4][2];
; #pragma unroll
;     for (int a = 0; a < 2; ++a)
; #pragma unroll
;         for (int b = 0; b < 2; ++b)
; #pragma unroll
;             for (int m = 0; m < 4; ++m)
; #pragma unroll
;                 for (int n = 0; n < 2; ++n) acc[a][b][m][n] = (f32x4){0.f, 0.f, 0.f, 0.f};
;     bf16x8 At[4][2], B0[2][2], B1[2][2];
;     const char* cA = (const char*)g.A + (size_t)cur.pm * tstep; const char* cB = (const char*)g.Bt + (size_t)cur.pn * tstep;
;     S.a_ready(cur);
;     if constexpr (SP2) {
;         PG8_STAGE(PG8_SB(0, 0), cB, voffB); PG8_STAGE(PG8_SB(0, 1), cB + hstep, voffB); PG8_STAGE(PG8_SA(0, 0), cA, voffA); PG8_STAGE(PG8_SA(0, 1), cA + hstep, voffA);
;         if (wr == 1) PG8_BAR;
;         PG8_WAIT_V(2); PG8_BAR;
;         PG8_STAGE(PG8_SB(1, 0), cB + kstep, voffB); PG8_STAGE(PG8_SA(1, 0), cA + kstep, voffA); PG8_STAGE(PG8_SB(1, 1), cB + hstep + kstep, voffB);
;         PG8_WAIT_V(6); PG8_BAR;
;     } else {
;         PG8_STAGE(PG8_SB(0, 0), cB, voffB); PG8_STAGE(PG8_SA(0, 0), cA, voffA); PG8_STAGE(PG8_SB(0, 1), cB + hstep, voffB); PG8_STAGE(PG8_SA(0, 1), cA + hstep, voffA);
;         if (wr == 1) PG8_BAR;
;         PG8_WAIT_V(4); PG8_BAR;
;         PG8_STAGE(PG8_SB(1, 0), cB + kstep, voffB); PG8_STAGE(PG8_SA(1, 0), cA + kstep, voffA); PG8_STAGE(PG8_SB(1, 1), cB + hstep + kstep, voffB);
;         PG8_WAIT_V(6); PG8_BAR;
;     }
.LBB0_1515:
	s_add_i32 s50, s3, 0x18000
	s_mov_b64 s[10:11], 0x80
	s_and_b32 s49, s6, 3
	v_lshl_add_u64 v[6:7], v[6:7], 0, s[10:11]
	s_mov_b32 m0, s50
	s_add_i32 s51, s3, 0x1a000
	s_lshl_b32 s6, s7, 13
	s_lshl_b32 s12, s49, 12
	s_waitcnt vmcnt(2)
	s_barrier
	global_load_lds_dwordx4 v[6:7], off
	v_lshl_add_u64 v[4:5], v[4:5], 0, s[10:11]
	s_mov_b32 m0, s51
	s_add_i32 s52, s3, 0x8000
	s_add_i32 s53, s3, 0xa000
	global_load_lds_dwordx4 v[4:5], off
	v_lshl_add_u64 v[2:3], v[2:3], 0, s[10:11]
	s_mov_b32 m0, s52
	s_add_u32 s8, s44, 0x40080
	global_load_lds_dwordx4 v[2:3], off
	v_lshl_add_u64 v[0:1], v[0:1], 0, s[10:11]
	s_mov_b32 m0, s53
	s_addc_u32 s9, s45, 0
	s_add_i32 s54, s3, 0x1c000
	global_load_lds_dwordx4 v[0:1], off
	v_lshl_add_u64 v[0:1], s[8:9], 0, v[130:131]
	s_mov_b32 m0, s54
	s_add_i32 s55, s3, 0x1e000
	global_load_lds_dwordx4 v[0:1], off
	v_lshl_add_u64 v[0:1], s[8:9], 0, v[134:135]
	s_mov_b32 m0, s55
	s_mov_b32 s56, 0
	global_load_lds_dwordx4 v[0:1], off
	v_bfe_u32 v0, v8, 4, 2
	v_and_b32_e32 v1, 15, v8
	v_lshlrev_b32_e32 v3, 4, v0
	v_lshl_or_b32 v146, s7, 6, v1
	v_lshl_or_b32 v1, v1, 6, v3
	v_lshlrev_b32_e32 v3, 2, v8
	v_and_b32_e32 v3, 32, v3
	v_lshlrev_b32_e32 v2, 3, v0
	v_bitop3_b32 v147, v1, s6, v3 bitop3:0xde
	v_cmp_eq_u32_e64 s[6:7], 0, v0
	v_lshlrev_b32_e32 v0, 14, v9
	v_and_b32_e32 v0, 0xffff8000, v0
	v_lshl_or_b32 v148, s49, 5, v2
	v_lshl_add_u32 v0, v10, 11, v0
	v_and_b32_e32 v2, 1, v9
	v_lshl_or_b32 v0, v2, 6, v0
	v_lshl_add_u32 v138, v11, 1, v0
	v_lshlrev_b32_e32 v0, 14, v12
	v_and_b32_e32 v0, 0xffff8000, v0
	s_waitcnt vmcnt(6)
	v_lshl_add_u32 v0, v13, 11, v0
	v_and_b32_e32 v2, 1, v12
	v_bitop3_b32 v1, v1, s12, v3 bitop3:0xde
	v_lshl_or_b32 v0, v2, 6, v0
	s_ashr_i32 s57, s28, 31
	s_mov_b32 s58, s28
	s_ashr_i32 s59, s26, 31
	v_mov_b32_e32 v139, v137
	v_lshl_add_u32 v140, v14, 1, v0
	v_mov_b32_e32 v141, v137
	v_mov_b64_e32 v[142:143], 0x100
	v_mov_b64_e32 v[144:145], 0xff
	v_or_b32_e32 v149, 0x10000, v1
	v_add_u32_e32 v150, 0x10400, v1
	v_add_u32_e32 v151, 0x10800, v1
	v_add_u32_e32 v152, 0x10c00, v1
	v_or_b32_e32 v153, 0x14000, v1
	v_add_u32_e32 v154, 0x14400, v1
	v_add_u32_e32 v155, 0x14800, v1
	v_add_u32_e32 v156, 0x14c00, v1
	s_add_i32 s60, s3, 0xc000
	s_add_i32 s61, s3, 0xe000
	v_or_b32_e32 v157, 0x18000, v1
	v_add_u32_e32 v158, 0x18400, v1
	v_add_u32_e32 v159, 0x18800, v1
	s_waitcnt vmcnt(0)
	v_add_u32_e32 v160, 0x18c00, v1
	v_or_b32_e32 v161, 0x1c000, v1
	v_add_u32_e32 v162, 0x1c400, v1
	v_add_u32_e32 v163, 0x1c800, v1
	v_add_u32_e32 v164, 0x1cc00, v1
	v_mbcnt_hi_u32_b32 v165, -1, v226
	s_barrier
	s_mov_b32 s99, 0
	s_branch .LBB0_1517

; #define PG8_STAGE(bufoff, gbase, voff) do { _Pragma("unroll") for (int _i = 0; _i < 2; ++_i) \
;         __builtin_amdgcn_global_load_lds((const unsigned*)((const char*)(gbase) + (voff)[_i]), (PG8_LAS unsigned*)(lds + (bufoff) + ldsw + _i * 8192), 16, 0, 0); } while (0)
; #define PG8_LDA(dst, b, h) do { _Pragma("unroll") for (int m = 0; m < 4; ++m) _Pragma("unroll") for (int k = 0; k < 2; ++k) dst[m][k] = *(const PG8_LAS bf16x8*)(lds + PG8_SA(b, h) + aoff + m * 2048 + k * 1024); } while (0)
; #define PG8_LDB(dst, b, h) do { _Pragma("unroll") for (int n = 0; n < 2; ++n) _Pragma("unroll") for (int k = 0; k < 2; ++k) dst[n][k] = *(const PG8_LAS bf16x8*)(lds + PG8_SB(b, h) + boff + n * 2048 + k * 1024); } while (0)
; #define PG8_MMA(ai, bj, At, Bt) do { __builtin_amdgcn_s_setprio(1); _Pragma("unroll") for (int m = 0; m < 4; ++m) _Pragma("unroll") for (int n = 0; n < 2; ++n) _Pragma("unroll") for (int k = 0; k < 2; ++k) \
;         acc[ai][bj][m][n] = mma16<F16>(Bt[n][k], At[m][k], acc[ai][bj][m][n]); __builtin_amdgcn_s_setprio(0); } while (0)
; #define PG8_WAIT_V(n) asm volatile("s_waitcnt vmcnt(" #n ")" ::: "memory")
; #define PG8_WAIT_L(n) asm volatile("s_waitcnt lgkmcnt(" #n ")" ::: "memory")
; #define PG8_BAR __builtin_amdgcn_s_barrier()
; #define PG8_SCHED __builtin_amdgcn_sched_barrier(0)
; template <class Epi, class Sched, bool ALIGN_EPI = false, bool SP2 = false, bool F16 = false, bool TOKPERM = false>
; __device__ __forceinline__ void gemm_phase(PG8_LAS unsigned char* lds, const Gemm g, const Sched& S, const Epi& E, int wv) {
;     ...
;             PG8_LDB(B0, 0, 0); PG8_LDB(B1, 0, 1); PG8_SCHED; PG8_LDA(At, 0, 0); PG8_STAGE(PG8_SA(1, 1), a1 + hstep, voffA);
;             PG8_WAIT_V(8); PG8_WAIT_L(0); PG8_BAR; PG8_MMA(0, 0, At, B0); PG8_MMA(0, 1, At, B1); PG8_BAR; PG8_SCHED;
;             PG8_LDA(At, 0, 1); PG8_STAGE(PG8_SB(0, 0), b2, voffB); PG8_STAGE(PG8_SB(0, 1), b2 + hstep, voffB); PG8_STAGE(PG8_SA(0, 0), a2, voffA);
;             PG8_WAIT_V(8); PG8_WAIT_L(0); PG8_BAR; PG8_MMA(1, 0, At, B0); PG8_MMA(1, 1, At, B1); PG8_BAR; PG8_SCHED;
.LBB0_1524:
	ds_read_b128 v[166:169], v149
	ds_read_b128 v[170:173], v150
	ds_read_b128 v[174:177], v151
	ds_read_b128 v[178:181], v152
	ds_read_b128 v[182:185], v153
	ds_read_b128 v[186:189], v154
	ds_read_b128 v[190:193], v155
	ds_read_b128 v[194:197], v156
	s_add_u32 s44, s24, 0xfffc0080
	s_addc_u32 s45, s25, -1
	s_cmp_eq_u32 s65, 12
	s_cselect_b32 s47, s15, s45
	s_cselect_b32 s46, s21, s44
	s_cselect_b32 s45, s13, s64
	s_cselect_b32 s44, s62, s63
	s_mov_b32 m0, s60
	v_lshl_add_u64 v[232:233], s[24:25], 0, v[138:139]
	ds_read_b128 v[198:201], v147
	ds_read_b128 v[202:205], v147 offset:1024
	ds_read_b128 v[206:209], v147 offset:2048
	ds_read_b128 v[210:213], v147 offset:3072
	ds_read_b128 v[214:217], v147 offset:4096
	ds_read_b128 v[218:221], v147 offset:5120
	ds_read_b128 v[222:225], v147 offset:6144
	ds_read_b128 v[228:231], v147 offset:7168
	global_load_lds_dwordx4 v[232:233], off
	v_lshl_add_u64 v[232:233], s[24:25], 0, v[140:141]
	s_mov_b32 m0, s61
	s_nop 0
	global_load_lds_dwordx4 v[232:233], off
	s_waitcnt vmcnt(24)
	s_cmp_eq_u32 s99, 1
	s_cbranch_scc1 .Lvmw_1524_0
	s_waitcnt vmcnt(8)
.Lvmw_1524_0:
	s_waitcnt lgkmcnt(0)
	s_barrier
	s_setprio 1
	s_waitcnt lgkmcnt(0)
	v_mfma_f32_16x16x32_bf16 v[124:127], v[166:169], v[198:201], v[124:127]
	v_mfma_f32_16x16x32_bf16 v[120:123], v[174:177], v[198:201], v[120:123]
	v_mfma_f32_16x16x32_bf16 v[108:111], v[166:169], v[206:209], v[108:111]
	v_mfma_f32_16x16x32_bf16 v[104:107], v[174:177], v[206:209], v[104:107]
	v_mfma_f32_16x16x32_bf16 v[92:95], v[166:169], v[214:217], v[92:95]
	v_mfma_f32_16x16x32_bf16 v[88:91], v[174:177], v[214:217], v[88:91]
	v_mfma_f32_16x16x32_bf16 v[76:79], v[166:169], v[222:225], v[76:79]
	v_mfma_f32_16x16x32_bf16 v[72:75], v[174:177], v[222:225], v[72:75]
	v_mfma_f32_16x16x32_bf16 v[124:127], v[170:173], v[202:205], v[124:127]
	v_mfma_f32_16x16x32_bf16 v[120:123], v[178:181], v[202:205], v[120:123]
	v_mfma_f32_16x16x32_bf16 v[108:111], v[170:173], v[210:213], v[108:111]
	v_mfma_f32_16x16x32_bf16 v[104:107], v[178:181], v[210:213], v[104:107]
	v_mfma_f32_16x16x32_bf16 v[92:95], v[170:173], v[218:221], v[92:95]
	v_mfma_f32_16x16x32_bf16 v[88:91], v[178:181], v[218:221], v[88:91]
	v_mfma_f32_16x16x32_bf16 v[76:79], v[170:173], v[228:231], v[76:79]
	v_mfma_f32_16x16x32_bf16 v[72:75], v[178:181], v[228:231], v[72:75]
	s_setprio 0
	s_setprio 1
	v_mfma_f32_16x16x32_bf16 v[116:119], v[182:185], v[198:201], v[116:119]
	v_mfma_f32_16x16x32_bf16 v[112:115], v[190:193], v[198:201], v[112:115]
	v_mfma_f32_16x16x32_bf16 v[100:103], v[182:185], v[206:209], v[100:103]
	v_mfma_f32_16x16x32_bf16 v[96:99], v[190:193], v[206:209], v[96:99]
	v_mfma_f32_16x16x32_bf16 v[84:87], v[182:185], v[214:217], v[84:87]
	v_mfma_f32_16x16x32_bf16 v[80:83], v[190:193], v[214:217], v[80:83]
	v_mfma_f32_16x16x32_bf16 v[68:71], v[182:185], v[222:225], v[68:71]
	v_mfma_f32_16x16x32_bf16 v[64:67], v[190:193], v[222:225], v[64:67]
	v_mfma_f32_16x16x32_bf16 v[116:119], v[186:189], v[202:205], v[116:119]
	v_mfma_f32_16x16x32_bf16 v[112:115], v[194:197], v[202:205], v[112:115]
	v_mfma_f32_16x16x32_bf16 v[100:103], v[186:189], v[210:213], v[100:103]
	v_mfma_f32_16x16x32_bf16 v[96:99], v[194:197], v[210:213], v[96:99]
	v_mfma_f32_16x16x32_bf16 v[84:87], v[186:189], v[218:221], v[84:87]
	v_mfma_f32_16x16x32_bf16 v[80:83], v[194:197], v[218:221], v[80:83]
	v_mfma_f32_16x16x32_bf16 v[68:71], v[186:189], v[228:231], v[68:71]
	v_mfma_f32_16x16x32_bf16 v[64:67], v[194:197], v[228:231], v[64:67]
	s_setprio 0
	s_barrier
	s_mov_b32 m0, s4
	v_lshl_add_u64 v[232:233], s[44:45], 0, v[130:131]
	s_add_u32 s66, s44, 0x40000
	ds_read_b128 v[198:201], v147 offset:16384
	ds_read_b128 v[202:205], v147 offset:17408
	ds_read_b128 v[206:209], v147 offset:18432
	ds_read_b128 v[210:213], v147 offset:19456
	ds_read_b128 v[214:217], v147 offset:20480
	ds_read_b128 v[218:221], v147 offset:21504
	ds_read_b128 v[222:225], v147 offset:22528
	ds_read_b128 v[228:231], v147 offset:23552
	global_load_lds_dwordx4 v[232:233], off
	v_lshl_add_u64 v[234:235], s[44:45], 0, v[134:135]
	s_mov_b32 m0, s5
	s_addc_u32 s67, s45, 0
	global_load_lds_dwordx4 v[234:235], off
	v_lshl_add_u64 v[236:237], s[66:67], 0, v[130:131]
	s_mov_b32 m0, s23
	v_lshl_add_u64 v[238:239], s[46:47], 0, v[132:133]
	global_load_lds_dwordx4 v[236:237], off
	v_lshl_add_u64 v[236:237], s[66:67], 0, v[134:135]
	s_mov_b32 m0, s33
	s_nop 0
	global_load_lds_dwordx4 v[236:237], off
	v_lshl_add_u64 v[236:237], s[46:47], 0, v[128:129]
	s_mov_b32 m0, s3
	s_nop 0
	global_load_lds_dwordx4 v[236:237], off
	s_mov_b32 m0, s36
	s_nop 0
	global_load_lds_dwordx4 v[238:239], off
	s_waitcnt vmcnt(24)
	s_cmp_eq_u32 s99, 1
	s_cbranch_scc1 .Lvmw_1524_1
	s_waitcnt vmcnt(8)
; #define PG8_STAGE(bufoff, gbase, voff) do { _Pragma("unroll") for (int _i = 0; _i < 2; ++_i) \
;         __builtin_amdgcn_global_load_lds((const unsigned*)((const char*)(gbase) + (voff)[_i]), (PG8_LAS unsigned*)(lds + (bufoff) + ldsw + _i * 8192), 16, 0, 0); } while (0)
; #define PG8_LDA(dst, b, h) do { _Pragma("unroll") for (int m = 0; m < 4; ++m) _Pragma("unroll") for (int k = 0; k < 2; ++k) dst[m][k] = *(const PG8_LAS bf16x8*)(lds + PG8_SA(b, h) + aoff + m * 2048 + k * 1024); } while (0)
; #define PG8_LDB(dst, b, h) do { _Pragma("unroll") for (int n = 0; n < 2; ++n) _Pragma("unroll") for (int k = 0; k < 2; ++k) dst[n][k] = *(const PG8_LAS bf16x8*)(lds + PG8_SB(b, h) + boff + n * 2048 + k * 1024); } while (0)
; #define PG8_MMA(ai, bj, At, Bt) do { __builtin_amdgcn_s_setprio(1); _Pragma("unroll") for (int m = 0; m < 4; ++m) _Pragma("unroll") for (int n = 0; n < 2; ++n) _Pragma("unroll") for (int k = 0; k < 2; ++k) \
;         acc[ai][bj][m][n] = mma16<F16>(Bt[n][k], At[m][k], acc[ai][bj][m][n]); __builtin_amdgcn_s_setprio(0); } while (0)
; #define PG8_WAIT_V(n) asm volatile("s_waitcnt vmcnt(" #n ")" ::: "memory")
; #define PG8_WAIT_L(n) asm volatile("s_waitcnt lgkmcnt(" #n ")" ::: "memory")
; #define PG8_BAR __builtin_amdgcn_s_barrier()
; #define PG8_SCHED __builtin_amdgcn_sched_barrier(0)
; template <class Epi, class Sched, bool ALIGN_EPI = false, bool SP2 = false, bool F16 = false, bool TOKPERM = false>
; __device__ __forceinline__ void gemm_phase(PG8_LAS unsigned char* lds, const Gemm g, const Sched& S, const Epi& E, int wv) {
;     ...
;             PG8_WAIT_V(8); PG8_WAIT_L(0); PG8_BAR; PG8_MMA(1, 0, At, B0); PG8_MMA(1, 1, At, B1); PG8_BAR; PG8_SCHED;
;             PG8_LDB(B0, 1, 0); PG8_LDB(B1, 1, 1); PG8_SCHED; PG8_LDA(At, 1, 0); PG8_STAGE(PG8_SA(0, 1), a2 + hstep, voffA);
;             PG8_WAIT_V(8); PG8_WAIT_L(0); PG8_BAR; PG8_MMA(0, 0, At, B0); PG8_MMA(0, 1, At, B1); PG8_BAR; PG8_SCHED;
.Lvmw_1524_1:
	s_mov_b32 s99, 0
	s_waitcnt lgkmcnt(0)
	s_barrier
	s_setprio 1
	s_waitcnt lgkmcnt(0)
	v_mfma_f32_16x16x32_bf16 v[60:63], v[166:169], v[198:201], v[60:63]
	v_mfma_f32_16x16x32_bf16 v[56:59], v[174:177], v[198:201], v[56:59]
	v_mfma_f32_16x16x32_bf16 v[44:47], v[166:169], v[206:209], v[44:47]
	v_mfma_f32_16x16x32_bf16 v[40:43], v[174:177], v[206:209], v[40:43]
	v_mfma_f32_16x16x32_bf16 v[28:31], v[166:169], v[214:217], v[28:31]
	v_mfma_f32_16x16x32_bf16 v[24:27], v[174:177], v[214:217], v[24:27]
	v_mfma_f32_16x16x32_bf16 v[12:15], v[166:169], v[222:225], v[12:15]
	v_mfma_f32_16x16x32_bf16 v[8:11], v[174:177], v[222:225], v[8:11]
	v_mfma_f32_16x16x32_bf16 v[60:63], v[170:173], v[202:205], v[60:63]
	v_mfma_f32_16x16x32_bf16 v[56:59], v[178:181], v[202:205], v[56:59]
	v_mfma_f32_16x16x32_bf16 v[44:47], v[170:173], v[210:213], v[44:47]
	v_mfma_f32_16x16x32_bf16 v[40:43], v[178:181], v[210:213], v[40:43]
	v_mfma_f32_16x16x32_bf16 v[28:31], v[170:173], v[218:221], v[28:31]
	v_mfma_f32_16x16x32_bf16 v[24:27], v[178:181], v[218:221], v[24:27]
	v_mfma_f32_16x16x32_bf16 v[12:15], v[170:173], v[228:231], v[12:15]
	v_mfma_f32_16x16x32_bf16 v[8:11], v[178:181], v[228:231], v[8:11]
	s_setprio 0
	s_setprio 1
	v_mfma_f32_16x16x32_bf16 v[52:55], v[182:185], v[198:201], v[52:55]
	v_mfma_f32_16x16x32_bf16 v[48:51], v[190:193], v[198:201], v[48:51]
	v_mfma_f32_16x16x32_bf16 v[36:39], v[182:185], v[206:209], v[36:39]
	v_mfma_f32_16x16x32_bf16 v[32:35], v[190:193], v[206:209], v[32:35]
	v_mfma_f32_16x16x32_bf16 v[20:23], v[182:185], v[214:217], v[20:23]
	v_mfma_f32_16x16x32_bf16 v[16:19], v[190:193], v[214:217], v[16:19]
	v_mfma_f32_16x16x32_bf16 v[4:7], v[182:185], v[222:225], v[4:7]
	v_mfma_f32_16x16x32_bf16 v[0:3], v[190:193], v[222:225], v[0:3]
	v_mfma_f32_16x16x32_bf16 v[52:55], v[186:189], v[202:205], v[52:55]
	v_mfma_f32_16x16x32_bf16 v[48:51], v[194:197], v[202:205], v[48:51]
	v_mfma_f32_16x16x32_bf16 v[36:39], v[186:189], v[210:213], v[36:39]
	v_mfma_f32_16x16x32_bf16 v[32:35], v[194:197], v[210:213], v[32:35]
	v_mfma_f32_16x16x32_bf16 v[20:23], v[186:189], v[218:221], v[20:23]
	v_mfma_f32_16x16x32_bf16 v[16:19], v[194:197], v[218:221], v[16:19]
	v_mfma_f32_16x16x32_bf16 v[4:7], v[186:189], v[228:231], v[4:7]
	v_mfma_f32_16x16x32_bf16 v[0:3], v[194:197], v[228:231], v[0:3]
	s_setprio 0
	s_barrier
	ds_read_b128 v[166:169], v157
	ds_read_b128 v[170:173], v158
	ds_read_b128 v[174:177], v159
	ds_read_b128 v[178:181], v160
	ds_read_b128 v[182:185], v161
	ds_read_b128 v[186:189], v162
	ds_read_b128 v[190:193], v163
	ds_read_b128 v[194:197], v164
	s_add_u32 s46, s46, 0x40000
	s_addc_u32 s47, s47, 0
	s_mov_b32 m0, s37
	v_lshl_add_u64 v[240:241], s[46:47], 0, v[128:129]
	ds_read_b128 v[198:201], v147 offset:32768
	ds_read_b128 v[202:205], v147 offset:33792
	ds_read_b128 v[206:209], v147 offset:34816
	ds_read_b128 v[210:213], v147 offset:35840
	ds_read_b128 v[214:217], v147 offset:36864
	ds_read_b128 v[218:221], v147 offset:37888
	ds_read_b128 v[222:225], v147 offset:38912
	ds_read_b128 v[228:231], v147 offset:39936
	global_load_lds_dwordx4 v[240:241], off
	v_lshl_add_u64 v[240:241], s[46:47], 0, v[132:133]
	s_mov_b32 m0, s48
	s_nop 0
	global_load_lds_dwordx4 v[240:241], off
	s_waitcnt vmcnt(8)
	s_waitcnt lgkmcnt(0)
	s_barrier
	s_setprio 1
	s_waitcnt lgkmcnt(0)
	v_mfma_f32_16x16x32_bf16 v[124:127], v[166:169], v[198:201], v[124:127]
	v_mfma_f32_16x16x32_bf16 v[120:123], v[174:177], v[198:201], v[120:123]
	v_mfma_f32_16x16x32_bf16 v[108:111], v[166:169], v[206:209], v[108:111]
	v_mfma_f32_16x16x32_bf16 v[104:107], v[174:177], v[206:209], v[104:107]
	v_mfma_f32_16x16x32_bf16 v[92:95], v[166:169], v[214:217], v[92:95]
	v_mfma_f32_16x16x32_bf16 v[88:91], v[174:177], v[214:217], v[88:91]
	v_mfma_f32_16x16x32_bf16 v[76:79], v[166:169], v[222:225], v[76:79]
	v_mfma_f32_16x16x32_bf16 v[72:75], v[174:177], v[222:225], v[72:75]
	v_mfma_f32_16x16x32_bf16 v[124:127], v[170:173], v[202:205], v[124:127]
	v_mfma_f32_16x16x32_bf16 v[120:123], v[178:181], v[202:205], v[120:123]
	v_mfma_f32_16x16x32_bf16 v[108:111], v[170:173], v[210:213], v[108:111]
	v_mfma_f32_16x16x32_bf16 v[104:107], v[178:181], v[210:213], v[104:107]
	v_mfma_f32_16x16x32_bf16 v[92:95], v[170:173], v[218:221], v[92:95]
	v_mfma_f32_16x16x32_bf16 v[88:91], v[178:181], v[218:221], v[88:91]
	v_mfma_f32_16x16x32_bf16 v[76:79], v[170:173], v[228:231], v[76:79]
	v_mfma_f32_16x16x32_bf16 v[72:75], v[178:181], v[228:231], v[72:75]
	s_setprio 0
	s_setprio 1
	v_mfma_f32_16x16x32_bf16 v[116:119], v[182:185], v[198:201], v[116:119]
	v_mfma_f32_16x16x32_bf16 v[112:115], v[190:193], v[198:201], v[112:115]
	v_mfma_f32_16x16x32_bf16 v[100:103], v[182:185], v[206:209], v[100:103]
	v_mfma_f32_16x16x32_bf16 v[96:99], v[190:193], v[206:209], v[96:99]
	v_mfma_f32_16x16x32_bf16 v[84:87], v[182:185], v[214:217], v[84:87]
	v_mfma_f32_16x16x32_bf16 v[80:83], v[190:193], v[214:217], v[80:83]
	v_mfma_f32_16x16x32_bf16 v[68:71], v[182:185], v[222:225], v[68:71]
	v_mfma_f32_16x16x32_bf16 v[64:67], v[190:193], v[222:225], v[64:67]
	v_mfma_f32_16x16x32_bf16 v[116:119], v[186:189], v[202:205], v[116:119]
	v_mfma_f32_16x16x32_bf16 v[112:115], v[194:197], v[202:205], v[112:115]
	v_mfma_f32_16x16x32_bf16 v[100:103], v[186:189], v[210:213], v[100:103]
	v_mfma_f32_16x16x32_bf16 v[96:99], v[194:197], v[210:213], v[96:99]
	v_mfma_f32_16x16x32_bf16 v[84:87], v[186:189], v[218:221], v[84:87]
	v_mfma_f32_16x16x32_bf16 v[80:83], v[194:197], v[218:221], v[80:83]
	v_mfma_f32_16x16x32_bf16 v[68:71], v[186:189], v[228:231], v[68:71]
	v_mfma_f32_16x16x32_bf16 v[64:67], v[194:197], v[228:231], v[64:67]
	s_setprio 0
	s_barrier
; #define PG8_STAGE(bufoff, gbase, voff) do { _Pragma("unroll") for (int _i = 0; _i < 2; ++_i) \
;         __builtin_amdgcn_global_load_lds((const unsigned*)((const char*)(gbase) + (voff)[_i]), (PG8_LAS unsigned*)(lds + (bufoff) + ldsw + _i * 8192), 16, 0, 0); } while (0)
; #define PG8_LDA(dst, b, h) do { _Pragma("unroll") for (int m = 0; m < 4; ++m) _Pragma("unroll") for (int k = 0; k < 2; ++k) dst[m][k] = *(const PG8_LAS bf16x8*)(lds + PG8_SA(b, h) + aoff + m * 2048 + k * 1024); } while (0)
; #define PG8_MMA(ai, bj, At, Bt) do { __builtin_amdgcn_s_setprio(1); _Pragma("unroll") for (int m = 0; m < 4; ++m) _Pragma("unroll") for (int n = 0; n < 2; ++n) _Pragma("unroll") for (int k = 0; k < 2; ++k) \
;         acc[ai][bj][m][n] = mma16<F16>(Bt[n][k], At[m][k], acc[ai][bj][m][n]); __builtin_amdgcn_s_setprio(0); } while (0)
; #define PG8_WAIT_V(n) asm volatile("s_waitcnt vmcnt(" #n ")" ::: "memory")
; #define PG8_WAIT_L(n) asm volatile("s_waitcnt lgkmcnt(" #n ")" ::: "memory")
; #define PG8_BAR __builtin_amdgcn_s_barrier()
; #define PG8_SCHED __builtin_amdgcn_sched_barrier(0)
; template <class Epi, class Sched, bool ALIGN_EPI = false, bool SP2 = false, bool F16 = false, bool TOKPERM = false>
; __device__ __forceinline__ void gemm_phase(PG8_LAS unsigned char* lds, const Gemm g, const Sched& S, const Epi& E, int wv) {
;     ...
;             PG8_LDA(At, 1, 1); PG8_STAGE(PG8_SB(1, 0), b3, voffB); PG8_STAGE(PG8_SB(1, 1), b3 + hstep, voffB); PG8_STAGE(PG8_SA(1, 0), a3, voffA);
;             PG8_WAIT_V(8); PG8_WAIT_L(0); PG8_BAR; PG8_MMA(1, 0, At, B0); PG8_MMA(1, 1, At, B1); PG8_BAR; PG8_SCHED;
	s_mov_b32 m0, s50
	v_lshl_add_u64 v[232:233], v[232:233], 0, s[10:11]
	s_add_u32 s44, s44, 0x40080
	ds_read_b128 v[198:201], v147 offset:49152
	ds_read_b128 v[202:205], v147 offset:50176
	ds_read_b128 v[206:209], v147 offset:51200
	ds_read_b128 v[210:213], v147 offset:52224
	ds_read_b128 v[214:217], v147 offset:53248
	ds_read_b128 v[218:221], v147 offset:54272
	ds_read_b128 v[222:225], v147 offset:55296
	ds_read_b128 v[228:231], v147 offset:56320
	global_load_lds_dwordx4 v[232:233], off
	v_lshl_add_u64 v[232:233], v[234:235], 0, s[10:11]
	s_mov_b32 m0, s51
	s_addc_u32 s45, s45, 0
	global_load_lds_dwordx4 v[232:233], off
	v_lshl_add_u64 v[232:233], s[44:45], 0, v[130:131]
	s_mov_b32 m0, s54
	s_nop 0
	global_load_lds_dwordx4 v[232:233], off
	v_lshl_add_u64 v[232:233], s[44:45], 0, v[134:135]
	s_mov_b32 m0, s55
	s_nop 0
	global_load_lds_dwordx4 v[232:233], off
	v_lshl_add_u64 v[232:233], v[236:237], 0, s[10:11]
	s_mov_b32 m0, s52
	s_nop 0
	global_load_lds_dwordx4 v[232:233], off
	v_lshl_add_u64 v[232:233], v[238:239], 0, s[10:11]
	s_mov_b32 m0, s53
	s_nop 0
	global_load_lds_dwordx4 v[232:233], off
	s_waitcnt vmcnt(8)
	s_waitcnt lgkmcnt(0)
	s_barrier
	s_setprio 1
	s_waitcnt lgkmcnt(0)
	v_mfma_f32_16x16x32_bf16 v[60:63], v[166:169], v[198:201], v[60:63]
	v_mfma_f32_16x16x32_bf16 v[56:59], v[174:177], v[198:201], v[56:59]
	v_mfma_f32_16x16x32_bf16 v[44:47], v[166:169], v[206:209], v[44:47]
	v_mfma_f32_16x16x32_bf16 v[40:43], v[174:177], v[206:209], v[40:43]
	v_mfma_f32_16x16x32_bf16 v[28:31], v[166:169], v[214:217], v[28:31]
	v_mfma_f32_16x16x32_bf16 v[24:27], v[174:177], v[214:217], v[24:27]
	v_mfma_f32_16x16x32_bf16 v[12:15], v[166:169], v[222:225], v[12:15]
	v_mfma_f32_16x16x32_bf16 v[8:11], v[174:177], v[222:225], v[8:11]
	v_mfma_f32_16x16x32_bf16 v[60:63], v[170:173], v[202:205], v[60:63]
	v_mfma_f32_16x16x32_bf16 v[56:59], v[178:181], v[202:205], v[56:59]
	v_mfma_f32_16x16x32_bf16 v[44:47], v[170:173], v[210:213], v[44:47]
	v_mfma_f32_16x16x32_bf16 v[40:43], v[178:181], v[210:213], v[40:43]
	v_mfma_f32_16x16x32_bf16 v[28:31], v[170:173], v[218:221], v[28:31]
	v_mfma_f32_16x16x32_bf16 v[24:27], v[178:181], v[218:221], v[24:27]
	v_mfma_f32_16x16x32_bf16 v[12:15], v[170:173], v[228:231], v[12:15]
	v_mfma_f32_16x16x32_bf16 v[8:11], v[178:181], v[228:231], v[8:11]
	s_setprio 0
	s_setprio 1
	v_mfma_f32_16x16x32_bf16 v[52:55], v[182:185], v[198:201], v[52:55]
	v_mfma_f32_16x16x32_bf16 v[48:51], v[190:193], v[198:201], v[48:51]
	v_mfma_f32_16x16x32_bf16 v[36:39], v[182:185], v[206:209], v[36:39]
	v_mfma_f32_16x16x32_bf16 v[32:35], v[190:193], v[206:209], v[32:35]
	v_mfma_f32_16x16x32_bf16 v[20:23], v[182:185], v[214:217], v[20:23]
	v_mfma_f32_16x16x32_bf16 v[16:19], v[190:193], v[214:217], v[16:19]
	v_mfma_f32_16x16x32_bf16 v[4:7], v[182:185], v[222:225], v[4:7]
	v_mfma_f32_16x16x32_bf16 v[0:3], v[190:193], v[222:225], v[0:3]
	v_mfma_f32_16x16x32_bf16 v[52:55], v[186:189], v[202:205], v[52:55]
	v_mfma_f32_16x16x32_bf16 v[48:51], v[194:197], v[202:205], v[48:51]
	v_mfma_f32_16x16x32_bf16 v[36:39], v[186:189], v[210:213], v[36:39]
	v_mfma_f32_16x16x32_bf16 v[32:35], v[194:197], v[210:213], v[32:35]
	v_mfma_f32_16x16x32_bf16 v[20:23], v[186:189], v[218:221], v[20:23]
	v_mfma_f32_16x16x32_bf16 v[16:19], v[194:197], v[218:221], v[16:19]
	v_mfma_f32_16x16x32_bf16 v[4:7], v[186:189], v[228:231], v[4:7]
	v_mfma_f32_16x16x32_bf16 v[0:3], v[194:197], v[228:231], v[0:3]
	s_setprio 0
	s_barrier
	s_add_i32 s65, s65, 2
	s_add_u32 s24, s24, 0x100
	s_addc_u32 s25, s25, 0
	s_add_u32 s63, s63, 0x100
	s_addc_u32 s64, s64, 0
	s_cmp_gt_u32 s65, 13
	s_cbranch_scc0 .LBB0_1524
;   __device__ __forceinline__ void operator()(const pg8::f32x4 (&acc)[2][2][4][2], const pg8::Unit& u, int wr, int wc, int fr, int fq) const {
;     int z; asm volatile("v_mov_b32 %0, 0" : "=v"(z));
;     const int row0 = u.pm * 256 + wr * 64 + fr + z, colb = u.pn * 256 + wc * 32 + 8 * fq + z;
; #pragma unroll
;     for (int ai = 0; ai < 2; ++ai)
; #pragma unroll
;       for (int m = 0; m < 4; ++m) {
;         const int tok = row0 + ai * 128 + m * 16; float ss = 0.f;
; #pragma unroll
;         for (int bj = 0; bj < 2; ++bj) {
;           const unsigned off = (unsigned)tok * DM + colb + 128 * bj;
;           f8_t n = __builtin_convertvector(*(const h8_t*)(x16 + off), f8_t);
; #pragma unroll
;           for (int c = 0; c < 4; ++c) { n[c] += sc * acc[ai][bj][m][0][c]; n[4 + c] += sc * acc[ai][bj][m][1][c]; }
;           if (aux) {
;             *(h8_t*)(x16 + off) = __builtin_convertvector(n, h8_t);
;             ss += ((n[0] * n[0] + n[1] * n[1]) + (n[2] * n[2] + n[3] * n[3])) + ((n[4] * n[4] + n[5] * n[5]) + (n[6] * n[6] + n[7] * n[7]));
;           } else {
;             *(f32x4*)(xout + off) = (f32x4){n[0], n[1], n[2], n[3]}; *(f32x4*)(xout + off + 4) = (f32x4){n[4], n[5], n[6], n[7]};
;           }
;         }
;         if (aux) { ss += __shfl_xor(ss, 16); ss += __shfl_xor(ss, 32); if (fq == 0) ssq[(unsigned)tok * 16 + u.pn * 4 + wc] = ss; }
;         if (m & 1) asm volatile("" ::: "memory");
;       }
;   }
	s_mov_b32 s99, 1
	s_lshl_b32 s13, s22, 8
	v_lshl_or_b32 v166, s20, 8, v148
	v_mov_b32 v136, 0
	v_xor_b32_e32 v169, 32, v165
	v_add3_u32 v167, s13, v146, v136
	v_add_u32_e32 v168, v166, v136
	v_lshl_add_u32 v136, v167, 10, v168
	v_lshl_add_u64 v[178:179], v[136:137], 1, s[40:41]
	v_add_u32_e32 v136, 0x80, v136
	global_load_dwordx4 v[170:173], v[178:179], off
	v_lshl_add_u64 v[180:181], v[136:137], 1, s[40:41]
	global_load_dwordx4 v[174:177], v[180:181], off
	v_add_u32_e32 v136, 16, v167
	v_lshl_add_u32 v136, v136, 10, v168
	v_lshl_add_u64 v[224:225], v[136:137], 1, s[40:41]
	v_add_u32_e32 v136, 0x80, v136
	global_load_dwordx4 v[192:195], v[224:225], off
	v_lshl_add_u64 v[248:249], v[136:137], 1, s[40:41]
	global_load_dwordx4 v[196:199], v[248:249], off
	v_add_u32_e32 v136, 32, v167
	v_lshl_add_u32 v136, v136, 10, v168
	v_lshl_add_u64 v[224:225], v[136:137], 1, s[40:41]
	v_add_u32_e32 v136, 0x80, v136
	global_load_dwordx4 v[200:203], v[224:225], off
	v_lshl_add_u64 v[248:249], v[136:137], 1, s[40:41]
	global_load_dwordx4 v[204:207], v[248:249], off
	v_add_u32_e32 v136, 48, v167
	v_lshl_add_u32 v136, v136, 10, v168
	v_lshl_add_u64 v[224:225], v[136:137], 1, s[40:41]
	v_add_u32_e32 v136, 0x80, v136
	global_load_dwordx4 v[208:211], v[224:225], off
	v_lshl_add_u64 v[248:249], v[136:137], 1, s[40:41]
	global_load_dwordx4 v[212:215], v[248:249], off
	v_add_u32_e32 v136, 0x80, v167
	v_lshl_add_u32 v136, v136, 10, v168
	v_lshl_add_u64 v[224:225], v[136:137], 1, s[40:41]
	v_add_u32_e32 v136, 0x80, v136
	global_load_dwordx4 v[216:219], v[224:225], off
	v_lshl_add_u64 v[248:249], v[136:137], 1, s[40:41]
	global_load_dwordx4 v[220:223], v[248:249], off
	v_add_u32_e32 v136, 0x90, v167
	v_lshl_add_u32 v136, v136, 10, v168
	v_lshl_add_u64 v[224:225], v[136:137], 1, s[40:41]
	v_add_u32_e32 v136, 0x80, v136
	global_load_dwordx4 v[228:231], v[224:225], off
	v_lshl_add_u64 v[248:249], v[136:137], 1, s[40:41]
	global_load_dwordx4 v[244:247], v[248:249], off
	v_and_b32_e32 v166, 64, v165
	v_xor_b32_e32 v136, 16, v165
	v_add_u32_e32 v166, 64, v166
	v_cmp_lt_i32_e32 vcc, v136, v166
	s_lshl_b32 s13, s20, 2
	s_or_b32 s13, s13, s49
	v_cndmask_b32_e32 v136, v165, v136, vcc
	v_cmp_lt_i32_e32 vcc, v169, v166
	v_lshlrev_b32_e32 v166, 2, v136
	s_waitcnt vmcnt(10)
	v_cvt_f32_f16_e32 v182, v173
	v_cvt_f32_f16_sdwa v183, v173 dst_sel:DWORD dst_unused:UNUSED_PAD src0_sel:WORD_1
	v_cvt_f32_f16_e32 v184, v171
	v_cvt_f32_f16_sdwa v185, v171 dst_sel:DWORD dst_unused:UNUSED_PAD src0_sel:WORD_1
	v_cvt_f32_f16_e32 v186, v172
	v_cvt_f32_f16_sdwa v187, v172 dst_sel:DWORD dst_unused:UNUSED_PAD src0_sel:WORD_1
	v_cvt_f32_f16_e32 v172, v170
	v_cvt_f32_f16_sdwa v173, v170 dst_sel:DWORD dst_unused:UNUSED_PAD src0_sel:WORD_1
	v_cvt_f32_f16_e32 v170, v177
	v_cvt_f32_f16_sdwa v171, v177 dst_sel:DWORD dst_unused:UNUSED_PAD src0_sel:WORD_1
	v_cvt_f32_f16_e32 v188, v175
	v_cvt_f32_f16_sdwa v189, v175 dst_sel:DWORD dst_unused:UNUSED_PAD src0_sel:WORD_1
	v_cvt_f32_f16_e32 v190, v176
	v_cvt_f32_f16_sdwa v191, v176 dst_sel:DWORD dst_unused:UNUSED_PAD src0_sel:WORD_1
	v_cvt_f32_f16_e32 v176, v174
	v_cvt_f32_f16_sdwa v177, v174 dst_sel:DWORD dst_unused:UNUSED_PAD src0_sel:WORD_1
	v_pk_add_f32 v[124:125], v[124:125], v[172:173]
	v_pk_add_f32 v[172:173], v[120:121], v[186:187]
	v_pk_add_f32 v[126:127], v[126:127], v[184:185]
	v_pk_add_f32 v[122:123], v[122:123], v[182:183]
	v_cvt_pk_f16_f32 v120, v172, v173
	v_cvt_pk_f16_f32 v121, v122, v123
	v_pk_mul_f32 v[174:175], v[124:125], v[124:125]
	v_pk_mul_f32 v[182:183], v[126:127], v[126:127]
	v_pk_fma_f32 v[174:175], v[172:173], v[172:173], v[174:175]
	v_pk_fma_f32 v[182:183], v[122:123], v[122:123], v[182:183]
	v_pk_add_f32 v[176:177], v[116:117], v[176:177]
	v_pk_add_f32 v[116:117], v[112:113], v[190:191]
	v_pk_add_f32 v[184:185], v[118:119], v[188:189]
	v_pk_add_f32 v[112:113], v[114:115], v[170:171]
	v_pk_fma_f32 v[174:175], v[176:177], v[176:177], v[174:175]
	v_pk_fma_f32 v[182:183], v[184:185], v[184:185], v[182:183]
	v_pk_fma_f32 v[174:175], v[116:117], v[116:117], v[174:175]
	v_pk_fma_f32 v[182:183], v[112:113], v[112:113], v[182:183]
	v_pk_add_f32 v[174:175], v[174:175], v[182:183]
	v_add_f32_e32 v114, v174, v175
	v_mov_b32_e32 v115, v114
	s_nop 1
	v_permlane16_swap_b32_e32 v114, v115
	v_cndmask_b32_e32 v169, v165, v169, vcc
	v_cvt_pk_f16_f32 v119, v126, v127
	v_cvt_pk_f16_f32 v118, v124, v125
	global_store_dwordx4 v[178:179], v[118:121], off
	s_nop 1
	v_cvt_pk_f16_f32 v119, v112, v113
	s_waitcnt lgkmcnt(0)
	v_add_f32_e32 v113, v114, v115
	v_lshlrev_b32_e32 v112, 2, v169
	v_mov_b32_e32 v114, v113
	s_nop 1
	v_permlane32_swap_b32_e32 v113, v114
	v_cvt_pk_f16_f32 v118, v116, v117
	v_cvt_pk_f16_f32 v117, v184, v185
	v_cvt_pk_f16_f32 v116, v176, v177
	global_store_dwordx4 v[180:181], v[116:119], off
	s_and_saveexec_b64 s[20:21], s[6:7]
	s_cbranch_execz .LBB0_1527
	v_lshl_add_u32 v136, v167, 4, s13
	s_waitcnt lgkmcnt(0)
	v_add_f32_e32 v113, v113, v114
	v_lshl_add_u64 v[114:115], v[136:137], 2, s[42:43]
	global_store_dword v[114:115], v113, off
